# loop-edge rotation: K-loop back edge taken before the trailing barrier (barrier moved to loop top / exit path) in all six GEMM loops
# baseline (speedup 1.0000x reference)
.LBB0_237:
	s_ashr_i32 s9, s8, 31
	s_lshl_b64 s[10:11], s[8:9], 19
	s_add_u32 s10, s49, s10
	s_addc_u32 s11, s52, s11
	s_ashr_i32 s7, s6, 31
	s_lshl_b64 s[12:13], s[6:7], 19
	s_add_u32 s12, s20, s12
	s_addc_u32 s13, s21, s13
	s_andn2_b64 vcc, exec, s[0:1]
	s_cbranch_vccnz .Lzk_2
	v_mov_b64_e32 v[2:3], 0xc00
	v_cmp_lt_i64_e32 vcc, s[18:19], v[2:3]
	s_and_b64 s[18:19], vcc, exec
	s_cselect_b32 s7, s11, s15
	s_cselect_b32 s9, s10, s14
	s_cselect_b32 s37, s13, s17
	s_cselect_b32 s38, s12, s16
	s_add_u32 s14, s14, 0x40080
	s_addc_u32 s15, s15, 0
	s_add_u32 s39, s16, 0x100
	v_mov_b32_e32 v2, 0
	v_mov_b32_e32 v218, 0xff800000
	v_mov_b32_e32 v155, 0xffffff80
	s_addc_u32 s40, s17, 0
	s_mov_b32 s16, 0
	v_mov_b32_e32 v3, v2
	v_mov_b32_e32 v4, v2
	v_mov_b32_e32 v5, v2
	v_mov_b32_e32 v6, v2
	v_mov_b32_e32 v7, v2
	v_mov_b32_e32 v8, v2
	v_mov_b32_e32 v9, v2
	v_mov_b32_e32 v22, v2
	v_mov_b32_e32 v23, v2
	v_mov_b32_e32 v24, v2
	v_mov_b32_e32 v25, v2
	v_mov_b32_e32 v18, v2
	v_mov_b32_e32 v19, v2
	v_mov_b32_e32 v20, v2
	v_mov_b32_e32 v21, v2
	v_mov_b32_e32 v38, v2
	v_mov_b32_e32 v39, v2
	v_mov_b32_e32 v40, v2
	v_mov_b32_e32 v41, v2
	v_mov_b32_e32 v34, v2
	v_mov_b32_e32 v35, v2
	v_mov_b32_e32 v36, v2
	v_mov_b32_e32 v37, v2
	v_mov_b32_e32 v54, v2
	v_mov_b32_e32 v55, v2
	v_mov_b32_e32 v56, v2
	v_mov_b32_e32 v57, v2
	v_mov_b32_e32 v50, v2
	v_mov_b32_e32 v51, v2
	v_mov_b32_e32 v52, v2
	v_mov_b32_e32 v53, v2
	v_mov_b32_e32 v14, v2
	v_mov_b32_e32 v15, v2
	v_mov_b32_e32 v16, v2
	v_mov_b32_e32 v17, v2
	v_mov_b32_e32 v10, v2
	v_mov_b32_e32 v11, v2
	v_mov_b32_e32 v12, v2
	v_mov_b32_e32 v13, v2
	v_mov_b32_e32 v30, v2
	v_mov_b32_e32 v31, v2
	v_mov_b32_e32 v32, v2
	v_mov_b32_e32 v33, v2
	v_mov_b32_e32 v26, v2
	v_mov_b32_e32 v27, v2
	v_mov_b32_e32 v28, v2
	v_mov_b32_e32 v29, v2
	v_mov_b32_e32 v46, v2
	v_mov_b32_e32 v47, v2
	v_mov_b32_e32 v48, v2
	v_mov_b32_e32 v49, v2
	v_mov_b32_e32 v42, v2
	v_mov_b32_e32 v43, v2
	v_mov_b32_e32 v44, v2
	v_mov_b32_e32 v45, v2
	v_mov_b32_e32 v62, v2
	v_mov_b32_e32 v63, v2
	v_mov_b32_e32 v64, v2
	v_mov_b32_e32 v65, v2
	v_mov_b32_e32 v58, v2
	v_mov_b32_e32 v59, v2
	v_mov_b32_e32 v60, v2
	v_mov_b32_e32 v61, v2
	v_mov_b32_e32 v70, v2
	v_mov_b32_e32 v71, v2
	v_mov_b32_e32 v72, v2
	v_mov_b32_e32 v73, v2
	v_mov_b32_e32 v66, v2
	v_mov_b32_e32 v67, v2
	v_mov_b32_e32 v68, v2
	v_mov_b32_e32 v69, v2
	v_mov_b32_e32 v86, v2
	v_mov_b32_e32 v87, v2
	v_mov_b32_e32 v88, v2
	v_mov_b32_e32 v89, v2
	v_mov_b32_e32 v82, v2
	v_mov_b32_e32 v83, v2
	v_mov_b32_e32 v84, v2
	v_mov_b32_e32 v85, v2
	v_mov_b32_e32 v102, v2
	v_mov_b32_e32 v103, v2
	v_mov_b32_e32 v104, v2
	v_mov_b32_e32 v105, v2
	v_mov_b32_e32 v98, v2
	v_mov_b32_e32 v99, v2
	v_mov_b32_e32 v100, v2
	v_mov_b32_e32 v101, v2
	v_mov_b32_e32 v118, v2
	v_mov_b32_e32 v119, v2
	v_mov_b32_e32 v120, v2
	v_mov_b32_e32 v121, v2
	v_mov_b32_e32 v114, v2
	v_mov_b32_e32 v115, v2
	v_mov_b32_e32 v116, v2
	v_mov_b32_e32 v117, v2
	v_mov_b32_e32 v78, v2
	v_mov_b32_e32 v79, v2
	v_mov_b32_e32 v80, v2
	v_mov_b32_e32 v81, v2
	v_mov_b32_e32 v74, v2
	v_mov_b32_e32 v75, v2
	v_mov_b32_e32 v76, v2
	v_mov_b32_e32 v77, v2
	v_mov_b32_e32 v94, v2
	v_mov_b32_e32 v95, v2
	v_mov_b32_e32 v96, v2
	v_mov_b32_e32 v97, v2
	v_mov_b32_e32 v90, v2
	v_mov_b32_e32 v91, v2
	v_mov_b32_e32 v92, v2
	v_mov_b32_e32 v93, v2
	v_mov_b32_e32 v110, v2
	v_mov_b32_e32 v111, v2
	v_mov_b32_e32 v112, v2
	v_mov_b32_e32 v113, v2
	v_mov_b32_e32 v106, v2
	v_mov_b32_e32 v107, v2
	v_mov_b32_e32 v108, v2
	v_mov_b32_e32 v109, v2
	v_mov_b32_e32 v126, v2
	v_mov_b32_e32 v127, v2
	v_mov_b32_e32 v128, v2
	v_mov_b32_e32 v129, v2
	v_mov_b32_e32 v122, v2
	v_mov_b32_e32 v123, v2
	v_mov_b32_e32 v124, v2
	v_mov_b32_e32 v125, v2
	s_mov_b64 s[74:75], 0x80
	s_branch .Lrot_0
.LBB0_239:
	s_barrier
.Lrot_0:
	s_add_i32 s41, s16, 2
	s_add_u32 s17, s14, 0xfffc0080
	s_addc_u32 s18, s15, -1
	s_add_i32 s42, 0, 0x10000
	v_add_u32_e32 v149, s42, v1
	ds_read_b128 v[156:159], v149
	ds_read_b128 v[160:163], v149 offset:1024
	ds_read_b128 v[164:167], v149 offset:2048
	ds_read_b128 v[168:171], v149 offset:3072
	s_cmp_eq_u32 s31, s16
	s_cselect_b32 s16, s38, s39
	s_cselect_b32 s19, s7, s18
	s_cselect_b32 s18, s9, s17
	s_cselect_b32 s17, s37, s40
	s_add_i32 m0, s23, 0xc000
	ds_read_b128 v[172:175], v151
	ds_read_b128 v[176:179], v151 offset:1024
	ds_read_b128 v[180:183], v151 offset:2048
	ds_read_b128 v[184:187], v151 offset:3072
	ds_read_b128 v[188:191], v151 offset:4096
	ds_read_b128 v[192:195], v151 offset:5120
	ds_read_b128 v[196:199], v151 offset:6144
	ds_read_b128 v[200:203], v151 offset:7168
	global_load_lds_dwordx4 v140, s[14:15]
	s_add_i32 m0, s23, 0xe000
	s_nop 0
	global_load_lds_dwordx4 v142, s[14:15]
	s_waitcnt lgkmcnt(8)
	s_barrier
	s_waitcnt lgkmcnt(0)
	s_setprio 1
	s_waitcnt lgkmcnt(0)
	v_mfma_f32_16x16x32_bf16 v[122:125], v[156:159], v[172:175], v[122:125]
	v_mfma_f32_16x16x32_bf16 v[126:129], v[164:167], v[172:175], v[126:129]
	v_mfma_f32_16x16x32_bf16 v[106:109], v[156:159], v[180:183], v[106:109]
	v_mfma_f32_16x16x32_bf16 v[110:113], v[164:167], v[180:183], v[110:113]
	v_mfma_f32_16x16x32_bf16 v[90:93], v[156:159], v[188:191], v[90:93]
	v_mfma_f32_16x16x32_bf16 v[94:97], v[164:167], v[188:191], v[94:97]
	v_mfma_f32_16x16x32_bf16 v[74:77], v[156:159], v[196:199], v[74:77]
	v_mfma_f32_16x16x32_bf16 v[78:81], v[164:167], v[196:199], v[78:81]
	v_mfma_f32_16x16x32_bf16 v[122:125], v[160:163], v[176:179], v[122:125]
	v_mfma_f32_16x16x32_bf16 v[126:129], v[168:171], v[176:179], v[126:129]
	v_mfma_f32_16x16x32_bf16 v[106:109], v[160:163], v[184:187], v[106:109]
	v_mfma_f32_16x16x32_bf16 v[110:113], v[168:171], v[184:187], v[110:113]
	v_mfma_f32_16x16x32_bf16 v[90:93], v[160:163], v[192:195], v[90:93]
	v_mfma_f32_16x16x32_bf16 v[94:97], v[168:171], v[192:195], v[94:97]
	v_mfma_f32_16x16x32_bf16 v[74:77], v[160:163], v[200:203], v[74:77]
	v_mfma_f32_16x16x32_bf16 v[78:81], v[168:171], v[200:203], v[78:81]
	s_setprio 0
	s_barrier
	s_add_i32 s44, 0, 0x14000
	s_add_i32 s42, s42, s22
	v_add_u32_e32 v149, s44, v1
	v_lshl_add_u64 v[230:231], s[16:17], 0, v[134:135]
	s_mov_b32 m0, s42
	ds_read_b128 v[204:207], v149
	ds_read_b128 v[208:211], v149 offset:1024
	ds_read_b128 v[212:215], v149 offset:2048
	ds_read_b128 v[226:229], v149 offset:3072
	global_load_lds_dwordx4 v[230:231], off
	v_lshl_add_u64 v[232:233], s[16:17], 0, v[130:131]
	s_add_i32 m0, s42, 0x2000
	s_nop 0
	global_load_lds_dwordx4 v[232:233], off
	s_barrier
	s_waitcnt lgkmcnt(0)
	s_setprio 1
	s_waitcnt lgkmcnt(0)
	v_mfma_f32_16x16x32_bf16 v[114:117], v[204:207], v[172:175], v[114:117]
	v_mfma_f32_16x16x32_bf16 v[118:121], v[212:215], v[172:175], v[118:121]
	v_mfma_f32_16x16x32_bf16 v[98:101], v[204:207], v[180:183], v[98:101]
	v_mfma_f32_16x16x32_bf16 v[102:105], v[212:215], v[180:183], v[102:105]
	v_mfma_f32_16x16x32_bf16 v[82:85], v[204:207], v[188:191], v[82:85]
	v_mfma_f32_16x16x32_bf16 v[86:89], v[212:215], v[188:191], v[86:89]
	v_mfma_f32_16x16x32_bf16 v[66:69], v[204:207], v[196:199], v[66:69]
	v_mfma_f32_16x16x32_bf16 v[70:73], v[212:215], v[196:199], v[70:73]
	v_mfma_f32_16x16x32_bf16 v[114:117], v[208:211], v[176:179], v[114:117]
	v_mfma_f32_16x16x32_bf16 v[118:121], v[226:229], v[176:179], v[118:121]
	v_mfma_f32_16x16x32_bf16 v[98:101], v[208:211], v[184:187], v[98:101]
	v_mfma_f32_16x16x32_bf16 v[102:105], v[226:229], v[184:187], v[102:105]
	v_mfma_f32_16x16x32_bf16 v[82:85], v[208:211], v[192:195], v[82:85]
	v_mfma_f32_16x16x32_bf16 v[86:89], v[226:229], v[192:195], v[86:89]
	v_mfma_f32_16x16x32_bf16 v[66:69], v[208:211], v[200:203], v[66:69]
	v_mfma_f32_16x16x32_bf16 v[70:73], v[226:229], v[200:203], v[70:73]
	s_setprio 0
	s_mov_b32 m0, s23
	v_lshl_add_u64 v[234:235], s[18:19], 0, v[136:137]
	s_barrier
	ds_read_b128 v[172:175], v151 offset:16384
	ds_read_b128 v[176:179], v151 offset:17408
	ds_read_b128 v[180:183], v151 offset:18432
	ds_read_b128 v[184:187], v151 offset:19456
	ds_read_b128 v[188:191], v151 offset:20480
	ds_read_b128 v[192:195], v151 offset:21504
	ds_read_b128 v[196:199], v151 offset:22528
	ds_read_b128 v[200:203], v151 offset:23552
	global_load_lds_dwordx4 v[234:235], off
	v_lshl_add_u64 v[236:237], s[18:19], 0, v[132:133]
	s_mov_b32 m0, s24
	s_nop 0
	global_load_lds_dwordx4 v[236:237], off
	s_barrier
	s_waitcnt lgkmcnt(0)
	s_setprio 1
	s_waitcnt lgkmcnt(0)
	v_mfma_f32_16x16x32_bf16 v[58:61], v[156:159], v[172:175], v[58:61]
	v_mfma_f32_16x16x32_bf16 v[62:65], v[164:167], v[172:175], v[62:65]
	v_mfma_f32_16x16x32_bf16 v[42:45], v[156:159], v[180:183], v[42:45]
	v_mfma_f32_16x16x32_bf16 v[46:49], v[164:167], v[180:183], v[46:49]
	v_mfma_f32_16x16x32_bf16 v[26:29], v[156:159], v[188:191], v[26:29]
	v_mfma_f32_16x16x32_bf16 v[30:33], v[164:167], v[188:191], v[30:33]
	v_mfma_f32_16x16x32_bf16 v[10:13], v[156:159], v[196:199], v[10:13]
	v_mfma_f32_16x16x32_bf16 v[14:17], v[164:167], v[196:199], v[14:17]
	v_mfma_f32_16x16x32_bf16 v[58:61], v[160:163], v[176:179], v[58:61]
	v_mfma_f32_16x16x32_bf16 v[62:65], v[168:171], v[176:179], v[62:65]
	v_mfma_f32_16x16x32_bf16 v[42:45], v[160:163], v[184:187], v[42:45]
	v_mfma_f32_16x16x32_bf16 v[46:49], v[168:171], v[184:187], v[46:49]
	v_mfma_f32_16x16x32_bf16 v[26:29], v[160:163], v[192:195], v[26:29]
	v_mfma_f32_16x16x32_bf16 v[30:33], v[168:171], v[192:195], v[30:33]
	v_mfma_f32_16x16x32_bf16 v[10:13], v[160:163], v[200:203], v[10:13]
	v_mfma_f32_16x16x32_bf16 v[14:17], v[168:171], v[200:203], v[14:17]
	s_setprio 0
	s_barrier
	s_add_u32 s42, s16, 0x40000
	s_addc_u32 s43, s17, 0
	s_add_i32 s44, s44, s22
	s_mov_b32 m0, s44
	s_nop 0
	global_load_lds_dwordx4 v134, s[42:43]
	s_add_i32 m0, s44, 0x2000
	s_nop 0
	global_load_lds_dwordx4 v130, s[42:43]
	s_cmp_eq_u32 s100, 0
	s_cbranch_scc1 .Lip_w4n
	s_waitcnt vmcnt(24)
	s_branch .Lip_w4d

.Lip_w6n:
	s_barrier
	s_waitcnt lgkmcnt(0)
	s_setprio 1
	s_waitcnt lgkmcnt(0)
	v_mfma_f32_16x16x32_bf16 v[114:117], v[204:207], v[172:175], v[114:117]
	v_mfma_f32_16x16x32_bf16 v[118:121], v[212:215], v[172:175], v[118:121]
	v_mfma_f32_16x16x32_bf16 v[98:101], v[204:207], v[180:183], v[98:101]
	v_mfma_f32_16x16x32_bf16 v[102:105], v[212:215], v[180:183], v[102:105]
	v_mfma_f32_16x16x32_bf16 v[82:85], v[204:207], v[188:191], v[82:85]
	v_mfma_f32_16x16x32_bf16 v[86:89], v[212:215], v[188:191], v[86:89]
	v_mfma_f32_16x16x32_bf16 v[66:69], v[204:207], v[196:199], v[66:69]
	v_mfma_f32_16x16x32_bf16 v[70:73], v[212:215], v[196:199], v[70:73]
	v_mfma_f32_16x16x32_bf16 v[114:117], v[208:211], v[176:179], v[114:117]
	v_mfma_f32_16x16x32_bf16 v[118:121], v[226:229], v[176:179], v[118:121]
	v_mfma_f32_16x16x32_bf16 v[98:101], v[208:211], v[184:187], v[98:101]
	v_mfma_f32_16x16x32_bf16 v[102:105], v[226:229], v[184:187], v[102:105]
	v_mfma_f32_16x16x32_bf16 v[82:85], v[208:211], v[192:195], v[82:85]
	v_mfma_f32_16x16x32_bf16 v[86:89], v[226:229], v[192:195], v[86:89]
	v_mfma_f32_16x16x32_bf16 v[66:69], v[208:211], v[200:203], v[66:69]
	v_mfma_f32_16x16x32_bf16 v[70:73], v[226:229], v[200:203], v[70:73]
	s_setprio 0
	s_mov_b32 m0, s28
	v_lshl_add_u64 v[230:231], v[234:235], 0, s[74:75]
	s_barrier
	ds_read_b128 v[172:175], v151 offset:49152
	ds_read_b128 v[176:179], v151 offset:50176
	ds_read_b128 v[180:183], v151 offset:51200
	ds_read_b128 v[184:187], v151 offset:52224
	ds_read_b128 v[188:191], v151 offset:53248
	ds_read_b128 v[192:195], v151 offset:54272
	ds_read_b128 v[196:199], v151 offset:55296
	ds_read_b128 v[200:203], v151 offset:56320
	global_load_lds_dwordx4 v[230:231], off
	v_lshl_add_u64 v[230:231], v[236:237], 0, s[74:75]
	s_mov_b32 m0, s29
	s_nop 0
	global_load_lds_dwordx4 v[230:231], off
	s_barrier
	s_waitcnt lgkmcnt(0)
	s_setprio 1
	s_waitcnt lgkmcnt(0)
	v_mfma_f32_16x16x32_bf16 v[58:61], v[156:159], v[172:175], v[58:61]
	v_mfma_f32_16x16x32_bf16 v[62:65], v[164:167], v[172:175], v[62:65]
	v_mfma_f32_16x16x32_bf16 v[42:45], v[156:159], v[180:183], v[42:45]
	v_mfma_f32_16x16x32_bf16 v[46:49], v[164:167], v[180:183], v[46:49]
	v_mfma_f32_16x16x32_bf16 v[26:29], v[156:159], v[188:191], v[26:29]
	v_mfma_f32_16x16x32_bf16 v[30:33], v[164:167], v[188:191], v[30:33]
	v_mfma_f32_16x16x32_bf16 v[10:13], v[156:159], v[196:199], v[10:13]
	v_mfma_f32_16x16x32_bf16 v[14:17], v[164:167], v[196:199], v[14:17]
	v_mfma_f32_16x16x32_bf16 v[58:61], v[160:163], v[176:179], v[58:61]
	v_mfma_f32_16x16x32_bf16 v[62:65], v[168:171], v[176:179], v[62:65]
	v_mfma_f32_16x16x32_bf16 v[42:45], v[160:163], v[184:187], v[42:45]
	v_mfma_f32_16x16x32_bf16 v[46:49], v[168:171], v[184:187], v[46:49]
	v_mfma_f32_16x16x32_bf16 v[26:29], v[160:163], v[192:195], v[26:29]
	v_mfma_f32_16x16x32_bf16 v[30:33], v[168:171], v[192:195], v[30:33]
	v_mfma_f32_16x16x32_bf16 v[10:13], v[160:163], v[200:203], v[10:13]
	v_mfma_f32_16x16x32_bf16 v[14:17], v[168:171], v[200:203], v[14:17]
	s_setprio 0
	s_barrier
	s_add_u32 s16, s16, 0x40080
	s_addc_u32 s17, s17, 0
	s_add_i32 s18, s18, s22
	s_mov_b32 m0, s18
	s_nop 0
	global_load_lds_dwordx4 v134, s[16:17]
	s_add_i32 m0, s18, 0x2000
	s_nop 0
	global_load_lds_dwordx4 v130, s[16:17]
	s_waitcnt vmcnt(6)
	s_barrier
	s_setprio 1
	v_mfma_f32_16x16x32_bf16 v[50:53], v[204:207], v[172:175], v[50:53]
	v_mfma_f32_16x16x32_bf16 v[54:57], v[212:215], v[172:175], v[54:57]
	v_mfma_f32_16x16x32_bf16 v[34:37], v[204:207], v[180:183], v[34:37]
	v_mfma_f32_16x16x32_bf16 v[38:41], v[212:215], v[180:183], v[38:41]
	v_mfma_f32_16x16x32_bf16 v[18:21], v[204:207], v[188:191], v[18:21]
	v_mfma_f32_16x16x32_bf16 v[22:25], v[212:215], v[188:191], v[22:25]
	v_mfma_f32_16x16x32_bf16 v[6:9], v[204:207], v[196:199], v[6:9]
	v_mfma_f32_16x16x32_bf16 v[2:5], v[212:215], v[196:199], v[2:5]
	v_mfma_f32_16x16x32_bf16 v[50:53], v[208:211], v[176:179], v[50:53]
	v_mfma_f32_16x16x32_bf16 v[54:57], v[226:229], v[176:179], v[54:57]
	v_mfma_f32_16x16x32_bf16 v[34:37], v[208:211], v[184:187], v[34:37]
	v_mfma_f32_16x16x32_bf16 v[38:41], v[226:229], v[184:187], v[38:41]
	v_mfma_f32_16x16x32_bf16 v[18:21], v[208:211], v[192:195], v[18:21]
	v_mfma_f32_16x16x32_bf16 v[22:25], v[226:229], v[192:195], v[22:25]
	v_mfma_f32_16x16x32_bf16 v[6:9], v[208:211], v[200:203], v[6:9]
	v_mfma_f32_16x16x32_bf16 v[2:5], v[226:229], v[200:203], v[2:5]
	s_setprio 0
	s_add_u32 s14, s14, 0x100
	s_addc_u32 s15, s15, 0
	s_add_u32 s39, s39, 0x100
	s_addc_u32 s40, s40, 0
	s_cmp_ge_i32 s41, s27
	s_mov_b32 s16, s41
	s_cbranch_scc0 .LBB0_239
	s_barrier
	v_readlane_b32 s38, v255, 8
	v_mov_b32_e32 v203, v155
	v_readlane_b32 s39, v255, 9
	s_cmp_lt_i32 s35, 32
	s_mov_b64 s[14:15], -1
	s_cbranch_scc1 .LBB0_243

.LBB0_408:
	s_ashr_i32 s15, s14, 31
	s_lshl_b64 s[16:17], s[14:15], 17
	v_readlane_b32 s13, v254, 21
	s_add_u32 s13, s13, s16
	v_readlane_b32 s15, v254, 22
	s_addc_u32 s15, s15, s17
	s_ashr_i32 s16, s12, 4
	s_ashr_i32 s17, s16, 31
	s_lshl_b64 s[18:19], s[16:17], 8
	s_add_u32 s16, s13, s18
	s_addc_u32 s17, s15, s19
	s_ashr_i32 s13, s12, 31
	s_lshl_b64 s[40:41], s[12:13], 17
	s_add_u32 s13, s24, s40
	s_addc_u32 s15, s25, s41
	s_add_u32 s18, s13, s18
	s_addc_u32 s19, s15, s19
	s_andn2_b64 vcc, exec, s[10:11]
	s_cbranch_vccnz .Lzk_3
	v_mov_b64_e32 v[2:3], 0x500
	v_cmp_lt_i64_e32 vcc, s[22:23], v[2:3]
	s_and_b64 s[22:23], vcc, exec
	s_cselect_b32 s13, s17, s7
	s_cselect_b32 s15, s16, s6
	s_cselect_b32 s40, s19, s21
	s_cselect_b32 s41, s18, s20
	s_add_u32 s6, s6, 0x10080
	s_addc_u32 s7, s7, 0
	s_add_u32 s42, s20, 0x100
	v_mov_b32_e32 v2, 0
	v_mov_b32_e32 v218, 0xff800000
	v_mov_b32_e32 v216, 0xffffff80
	s_addc_u32 s43, s21, 0
	s_mov_b32 s20, 0
	v_mov_b32_e32 v3, v2
	v_mov_b32_e32 v4, v2
	v_mov_b32_e32 v5, v2
	v_mov_b32_e32 v6, v2
	v_mov_b32_e32 v7, v2
	v_mov_b32_e32 v8, v2
	v_mov_b32_e32 v9, v2
	v_mov_b32_e32 v18, v2
	v_mov_b32_e32 v19, v2
	v_mov_b32_e32 v20, v2
	v_mov_b32_e32 v21, v2
	v_mov_b32_e32 v22, v2
	v_mov_b32_e32 v23, v2
	v_mov_b32_e32 v24, v2
	v_mov_b32_e32 v25, v2
	v_mov_b32_e32 v34, v2
	v_mov_b32_e32 v35, v2
	v_mov_b32_e32 v36, v2
	v_mov_b32_e32 v37, v2
	v_mov_b32_e32 v38, v2
	v_mov_b32_e32 v39, v2
	v_mov_b32_e32 v40, v2
	v_mov_b32_e32 v41, v2
	v_mov_b32_e32 v50, v2
	v_mov_b32_e32 v51, v2
	v_mov_b32_e32 v52, v2
	v_mov_b32_e32 v53, v2
	v_mov_b32_e32 v54, v2
	v_mov_b32_e32 v55, v2
	v_mov_b32_e32 v56, v2
	v_mov_b32_e32 v57, v2
	v_mov_b32_e32 v10, v2
	v_mov_b32_e32 v11, v2
	v_mov_b32_e32 v12, v2
	v_mov_b32_e32 v13, v2
	v_mov_b32_e32 v14, v2
	v_mov_b32_e32 v15, v2
	v_mov_b32_e32 v16, v2
	v_mov_b32_e32 v17, v2
	v_mov_b32_e32 v26, v2
	v_mov_b32_e32 v27, v2
	v_mov_b32_e32 v28, v2
	v_mov_b32_e32 v29, v2
	v_mov_b32_e32 v30, v2
	v_mov_b32_e32 v31, v2
	v_mov_b32_e32 v32, v2
	v_mov_b32_e32 v33, v2
	v_mov_b32_e32 v42, v2
	v_mov_b32_e32 v43, v2
	v_mov_b32_e32 v44, v2
	v_mov_b32_e32 v45, v2
	v_mov_b32_e32 v46, v2
	v_mov_b32_e32 v47, v2
	v_mov_b32_e32 v48, v2
	v_mov_b32_e32 v49, v2
	v_mov_b32_e32 v58, v2
	v_mov_b32_e32 v59, v2
	v_mov_b32_e32 v60, v2
	v_mov_b32_e32 v61, v2
	v_mov_b32_e32 v62, v2
	v_mov_b32_e32 v63, v2
	v_mov_b32_e32 v64, v2
	v_mov_b32_e32 v65, v2
	v_mov_b32_e32 v66, v2
	v_mov_b32_e32 v67, v2
	v_mov_b32_e32 v68, v2
	v_mov_b32_e32 v69, v2
	v_mov_b32_e32 v70, v2
	v_mov_b32_e32 v71, v2
	v_mov_b32_e32 v72, v2
	v_mov_b32_e32 v73, v2
	v_mov_b32_e32 v82, v2
	v_mov_b32_e32 v83, v2
	v_mov_b32_e32 v84, v2
	v_mov_b32_e32 v85, v2
	v_mov_b32_e32 v90, v2
	v_mov_b32_e32 v91, v2
	v_mov_b32_e32 v92, v2
	v_mov_b32_e32 v93, v2
	v_mov_b32_e32 v114, v2
	v_mov_b32_e32 v115, v2
	v_mov_b32_e32 v116, v2
	v_mov_b32_e32 v117, v2
	v_mov_b32_e32 v118, v2
	v_mov_b32_e32 v119, v2
	v_mov_b32_e32 v120, v2
	v_mov_b32_e32 v121, v2
	v_mov_b32_e32 v130, v2
	v_mov_b32_e32 v131, v2
	v_mov_b32_e32 v132, v2
	v_mov_b32_e32 v133, v2
	v_mov_b32_e32 v134, v2
	v_mov_b32_e32 v135, v2
	v_mov_b32_e32 v136, v2
	v_mov_b32_e32 v137, v2
	v_mov_b32_e32 v74, v2
	v_mov_b32_e32 v75, v2
	v_mov_b32_e32 v76, v2
	v_mov_b32_e32 v77, v2
	v_mov_b32_e32 v78, v2
	v_mov_b32_e32 v79, v2
	v_mov_b32_e32 v80, v2
	v_mov_b32_e32 v81, v2
	v_mov_b32_e32 v102, v2
	v_mov_b32_e32 v103, v2
	v_mov_b32_e32 v104, v2
	v_mov_b32_e32 v105, v2
	v_mov_b32_e32 v110, v2
	v_mov_b32_e32 v111, v2
	v_mov_b32_e32 v112, v2
	v_mov_b32_e32 v113, v2
	v_mov_b32_e32 v122, v2
	v_mov_b32_e32 v123, v2
	v_mov_b32_e32 v124, v2
	v_mov_b32_e32 v125, v2
	v_mov_b32_e32 v126, v2
	v_mov_b32_e32 v127, v2
	v_mov_b32_e32 v128, v2
	v_mov_b32_e32 v129, v2
	v_mov_b32_e32 v138, v2
	v_mov_b32_e32 v139, v2
	v_mov_b32_e32 v140, v2
	v_mov_b32_e32 v141, v2
	v_mov_b32_e32 v148, v2
	v_mov_b32_e32 v149, v2
	v_mov_b32_e32 v150, v2
	v_mov_b32_e32 v151, v2
	s_mov_b64 s[74:75], 0x80
	s_branch .Lrot_1

.Lrot_1:
	s_add_i32 s44, s20, 2
	s_add_u32 s21, s6, 0xffff0080
	s_addc_u32 s22, s7, -1
	s_add_i32 s45, 0, 0x10000
	v_add_u32_e32 v106, s45, v166
	ds_read_b128 v[86:89], v106
	ds_read_b128 v[94:97], v106 offset:1024
	ds_read_b128 v[98:101], v106 offset:2048
	ds_read_b128 v[106:109], v106 offset:3072
	s_cmp_eq_u32 s36, s20
	s_cselect_b32 s20, s41, s42
	s_cselect_b32 s23, s13, s22
	s_cselect_b32 s22, s15, s21
	s_cselect_b32 s21, s40, s43
	s_add_i32 m0, s27, 0xc000
	ds_read_b128 v[162:165], v168
	ds_read_b128 v[170:173], v168 offset:1024
	ds_read_b128 v[174:177], v168 offset:2048
	ds_read_b128 v[178:181], v168 offset:3072
	ds_read_b128 v[182:185], v168 offset:4096
	ds_read_b128 v[186:189], v168 offset:5120
	ds_read_b128 v[190:193], v168 offset:6144
	ds_read_b128 v[194:197], v168 offset:7168
	global_load_lds_dwordx4 v158, s[6:7]
	s_add_i32 m0, s27, 0xe000
	s_nop 0
	global_load_lds_dwordx4 v160, s[6:7]
	s_waitcnt lgkmcnt(8)
	s_barrier
	s_waitcnt lgkmcnt(0)
	s_setprio 1
	s_waitcnt lgkmcnt(0)
	v_mfma_f32_16x16x32_bf16 v[148:151], v[86:89], v[162:165], v[148:151]
	v_mfma_f32_16x16x32_bf16 v[138:141], v[98:101], v[162:165], v[138:141]
	v_mfma_f32_16x16x32_bf16 v[126:129], v[86:89], v[174:177], v[126:129]
	v_mfma_f32_16x16x32_bf16 v[122:125], v[98:101], v[174:177], v[122:125]
	v_mfma_f32_16x16x32_bf16 v[110:113], v[86:89], v[182:185], v[110:113]
	v_mfma_f32_16x16x32_bf16 v[102:105], v[98:101], v[182:185], v[102:105]
	v_mfma_f32_16x16x32_bf16 v[78:81], v[86:89], v[190:193], v[78:81]
	v_mfma_f32_16x16x32_bf16 v[74:77], v[98:101], v[190:193], v[74:77]
	v_mfma_f32_16x16x32_bf16 v[148:151], v[94:97], v[170:173], v[148:151]
	v_mfma_f32_16x16x32_bf16 v[138:141], v[106:109], v[170:173], v[138:141]
	v_mfma_f32_16x16x32_bf16 v[126:129], v[94:97], v[178:181], v[126:129]
	v_mfma_f32_16x16x32_bf16 v[122:125], v[106:109], v[178:181], v[122:125]
	v_mfma_f32_16x16x32_bf16 v[110:113], v[94:97], v[186:189], v[110:113]
	v_mfma_f32_16x16x32_bf16 v[102:105], v[106:109], v[186:189], v[102:105]
	v_mfma_f32_16x16x32_bf16 v[78:81], v[94:97], v[194:197], v[78:81]
	v_mfma_f32_16x16x32_bf16 v[74:77], v[106:109], v[194:197], v[74:77]
	s_setprio 0
	s_barrier
	s_add_i32 s48, 0, 0x14000
	s_add_i32 s45, s45, s26
	v_add_u32_e32 v169, s48, v166
	v_lshl_add_u64 v[214:215], s[20:21], 0, v[154:155]
	s_mov_b32 m0, s45
	ds_read_b128 v[198:201], v169
	ds_read_b128 v[202:205], v169 offset:1024
	ds_read_b128 v[206:209], v169 offset:2048
	ds_read_b128 v[210:213], v169 offset:3072
	global_load_lds_dwordx4 v[214:215], off
	v_lshl_add_u64 v[226:227], s[20:21], 0, v[142:143]
	s_add_i32 m0, s45, 0x2000
	s_nop 0
	global_load_lds_dwordx4 v[226:227], off
	s_barrier
	s_waitcnt lgkmcnt(0)
	s_setprio 1
	s_waitcnt lgkmcnt(0)
	v_mfma_f32_16x16x32_bf16 v[134:137], v[198:201], v[162:165], v[134:137]
	v_mfma_f32_16x16x32_bf16 v[130:133], v[206:209], v[162:165], v[130:133]
	v_mfma_f32_16x16x32_bf16 v[118:121], v[198:201], v[174:177], v[118:121]
	v_mfma_f32_16x16x32_bf16 v[114:117], v[206:209], v[174:177], v[114:117]
	v_mfma_f32_16x16x32_bf16 v[90:93], v[198:201], v[182:185], v[90:93]
	v_mfma_f32_16x16x32_bf16 v[82:85], v[206:209], v[182:185], v[82:85]
	v_mfma_f32_16x16x32_bf16 v[70:73], v[198:201], v[190:193], v[70:73]
	v_mfma_f32_16x16x32_bf16 v[66:69], v[206:209], v[190:193], v[66:69]
	v_mfma_f32_16x16x32_bf16 v[134:137], v[202:205], v[170:173], v[134:137]
	v_mfma_f32_16x16x32_bf16 v[130:133], v[210:213], v[170:173], v[130:133]
	v_mfma_f32_16x16x32_bf16 v[118:121], v[202:205], v[178:181], v[118:121]
	v_mfma_f32_16x16x32_bf16 v[114:117], v[210:213], v[178:181], v[114:117]
	v_mfma_f32_16x16x32_bf16 v[90:93], v[202:205], v[186:189], v[90:93]
	v_mfma_f32_16x16x32_bf16 v[82:85], v[210:213], v[186:189], v[82:85]
	v_mfma_f32_16x16x32_bf16 v[70:73], v[202:205], v[194:197], v[70:73]
	v_mfma_f32_16x16x32_bf16 v[66:69], v[210:213], v[194:197], v[66:69]
	s_setprio 0
	s_mov_b32 m0, s27
	v_lshl_add_u64 v[228:229], s[22:23], 0, v[156:157]
	s_barrier
	ds_read_b128 v[162:165], v168 offset:16384
	ds_read_b128 v[170:173], v168 offset:17408
	ds_read_b128 v[174:177], v168 offset:18432
	ds_read_b128 v[178:181], v168 offset:19456
	ds_read_b128 v[182:185], v168 offset:20480
	ds_read_b128 v[186:189], v168 offset:21504
	ds_read_b128 v[190:193], v168 offset:22528
	ds_read_b128 v[194:197], v168 offset:23552
	global_load_lds_dwordx4 v[228:229], off
	v_lshl_add_u64 v[230:231], s[22:23], 0, v[152:153]
	s_mov_b32 m0, s28
	s_nop 0
	global_load_lds_dwordx4 v[230:231], off
	s_barrier
	s_waitcnt lgkmcnt(0)
	s_setprio 1
	s_waitcnt lgkmcnt(0)
	v_mfma_f32_16x16x32_bf16 v[62:65], v[86:89], v[162:165], v[62:65]
	v_mfma_f32_16x16x32_bf16 v[58:61], v[98:101], v[162:165], v[58:61]
	v_mfma_f32_16x16x32_bf16 v[46:49], v[86:89], v[174:177], v[46:49]
	v_mfma_f32_16x16x32_bf16 v[42:45], v[98:101], v[174:177], v[42:45]
	v_mfma_f32_16x16x32_bf16 v[30:33], v[86:89], v[182:185], v[30:33]
	v_mfma_f32_16x16x32_bf16 v[26:29], v[98:101], v[182:185], v[26:29]
	v_mfma_f32_16x16x32_bf16 v[14:17], v[86:89], v[190:193], v[14:17]
	v_mfma_f32_16x16x32_bf16 v[10:13], v[98:101], v[190:193], v[10:13]
	v_mfma_f32_16x16x32_bf16 v[62:65], v[94:97], v[170:173], v[62:65]
	v_mfma_f32_16x16x32_bf16 v[58:61], v[106:109], v[170:173], v[58:61]
	v_mfma_f32_16x16x32_bf16 v[46:49], v[94:97], v[178:181], v[46:49]
	v_mfma_f32_16x16x32_bf16 v[42:45], v[106:109], v[178:181], v[42:45]
	v_mfma_f32_16x16x32_bf16 v[30:33], v[94:97], v[186:189], v[30:33]
	v_mfma_f32_16x16x32_bf16 v[26:29], v[106:109], v[186:189], v[26:29]
	v_mfma_f32_16x16x32_bf16 v[14:17], v[94:97], v[194:197], v[14:17]
	v_mfma_f32_16x16x32_bf16 v[10:13], v[106:109], v[194:197], v[10:13]
	s_setprio 0
	s_barrier
	s_add_u32 s46, s20, 0x10000
	s_addc_u32 s47, s21, 0
	s_add_i32 s45, s48, s26
	s_mov_b32 m0, s45
	s_nop 0
	global_load_lds_dwordx4 v154, s[46:47]
	s_add_i32 m0, s45, 0x2000
	s_nop 0
	global_load_lds_dwordx4 v142, s[46:47]
	s_waitcnt vmcnt(6)
	s_barrier
	s_setprio 1
	v_mfma_f32_16x16x32_bf16 v[54:57], v[198:201], v[162:165], v[54:57]
	v_mfma_f32_16x16x32_bf16 v[50:53], v[206:209], v[162:165], v[50:53]
	v_mfma_f32_16x16x32_bf16 v[38:41], v[198:201], v[174:177], v[38:41]
	v_mfma_f32_16x16x32_bf16 v[34:37], v[206:209], v[174:177], v[34:37]
	v_mfma_f32_16x16x32_bf16 v[22:25], v[198:201], v[182:185], v[22:25]
	v_mfma_f32_16x16x32_bf16 v[18:21], v[206:209], v[182:185], v[18:21]
	v_mfma_f32_16x16x32_bf16 v[6:9], v[198:201], v[190:193], v[6:9]
	v_mfma_f32_16x16x32_bf16 v[2:5], v[206:209], v[190:193], v[2:5]
	v_mfma_f32_16x16x32_bf16 v[54:57], v[202:205], v[170:173], v[54:57]
	v_mfma_f32_16x16x32_bf16 v[50:53], v[210:213], v[170:173], v[50:53]
	v_mfma_f32_16x16x32_bf16 v[38:41], v[202:205], v[178:181], v[38:41]
	v_mfma_f32_16x16x32_bf16 v[34:37], v[210:213], v[178:181], v[34:37]
	v_mfma_f32_16x16x32_bf16 v[22:25], v[202:205], v[186:189], v[22:25]
	v_mfma_f32_16x16x32_bf16 v[18:21], v[210:213], v[186:189], v[18:21]
	v_mfma_f32_16x16x32_bf16 v[6:9], v[202:205], v[194:197], v[6:9]
	v_mfma_f32_16x16x32_bf16 v[2:5], v[210:213], v[194:197], v[2:5]
	s_setprio 0
	s_add_i32 s45, 0, 0x18000
	v_add_u32_e32 v106, s45, v166
	s_barrier
	ds_read_b128 v[86:89], v106
	ds_read_b128 v[94:97], v106 offset:1024
	ds_read_b128 v[98:101], v106 offset:2048
	ds_read_b128 v[106:109], v106 offset:3072
	s_add_u32 s22, s22, 0x10000
	s_addc_u32 s23, s23, 0
	s_mov_b32 m0, s29
	ds_read_b128 v[162:165], v168 offset:32768
	ds_read_b128 v[170:173], v168 offset:33792
	ds_read_b128 v[174:177], v168 offset:34816
	ds_read_b128 v[178:181], v168 offset:35840
	ds_read_b128 v[182:185], v168 offset:36864
	ds_read_b128 v[186:189], v168 offset:37888
	ds_read_b128 v[190:193], v168 offset:38912
	ds_read_b128 v[194:197], v168 offset:39936
	global_load_lds_dwordx4 v156, s[22:23]
	s_mov_b32 m0, s30
	s_nop 0
	global_load_lds_dwordx4 v152, s[22:23]
	s_waitcnt lgkmcnt(8)
	s_barrier
	s_waitcnt lgkmcnt(0)
	s_setprio 1
	s_waitcnt lgkmcnt(0)
	v_mfma_f32_16x16x32_bf16 v[148:151], v[86:89], v[162:165], v[148:151]
	v_mfma_f32_16x16x32_bf16 v[138:141], v[98:101], v[162:165], v[138:141]
	v_mfma_f32_16x16x32_bf16 v[126:129], v[86:89], v[174:177], v[126:129]
	v_mfma_f32_16x16x32_bf16 v[122:125], v[98:101], v[174:177], v[122:125]
	v_mfma_f32_16x16x32_bf16 v[110:113], v[86:89], v[182:185], v[110:113]
	v_mfma_f32_16x16x32_bf16 v[102:105], v[98:101], v[182:185], v[102:105]
	v_mfma_f32_16x16x32_bf16 v[78:81], v[86:89], v[190:193], v[78:81]
	v_mfma_f32_16x16x32_bf16 v[74:77], v[98:101], v[190:193], v[74:77]
	v_mfma_f32_16x16x32_bf16 v[148:151], v[94:97], v[170:173], v[148:151]
	v_mfma_f32_16x16x32_bf16 v[138:141], v[106:109], v[170:173], v[138:141]
	v_mfma_f32_16x16x32_bf16 v[126:129], v[94:97], v[178:181], v[126:129]
	v_mfma_f32_16x16x32_bf16 v[122:125], v[106:109], v[178:181], v[122:125]
	v_mfma_f32_16x16x32_bf16 v[110:113], v[94:97], v[186:189], v[110:113]
	v_mfma_f32_16x16x32_bf16 v[102:105], v[106:109], v[186:189], v[102:105]
	v_mfma_f32_16x16x32_bf16 v[78:81], v[94:97], v[194:197], v[78:81]
	v_mfma_f32_16x16x32_bf16 v[74:77], v[106:109], v[194:197], v[74:77]
	s_setprio 0
	s_barrier
	s_add_i32 s22, 0, 0x1c000
	s_add_i32 s23, s45, s26
	v_add_u32_e32 v169, s22, v166
	v_lshl_add_u64 v[214:215], v[214:215], 0, s[74:75]
	s_mov_b32 m0, s23
	ds_read_b128 v[198:201], v169
	ds_read_b128 v[202:205], v169 offset:1024
	ds_read_b128 v[206:209], v169 offset:2048
	ds_read_b128 v[210:213], v169 offset:3072
	global_load_lds_dwordx4 v[214:215], off
	v_lshl_add_u64 v[214:215], v[226:227], 0, s[74:75]
	s_add_i32 m0, s23, 0x2000
	s_nop 0
	global_load_lds_dwordx4 v[214:215], off
	s_barrier
	s_waitcnt lgkmcnt(0)
	s_setprio 1
	s_waitcnt lgkmcnt(0)
	v_mfma_f32_16x16x32_bf16 v[134:137], v[198:201], v[162:165], v[134:137]
	v_mfma_f32_16x16x32_bf16 v[130:133], v[206:209], v[162:165], v[130:133]
	v_mfma_f32_16x16x32_bf16 v[118:121], v[198:201], v[174:177], v[118:121]
	v_mfma_f32_16x16x32_bf16 v[114:117], v[206:209], v[174:177], v[114:117]
	v_mfma_f32_16x16x32_bf16 v[90:93], v[198:201], v[182:185], v[90:93]
	v_mfma_f32_16x16x32_bf16 v[82:85], v[206:209], v[182:185], v[82:85]
	v_mfma_f32_16x16x32_bf16 v[70:73], v[198:201], v[190:193], v[70:73]
	v_mfma_f32_16x16x32_bf16 v[66:69], v[206:209], v[190:193], v[66:69]
	v_mfma_f32_16x16x32_bf16 v[134:137], v[202:205], v[170:173], v[134:137]
	v_mfma_f32_16x16x32_bf16 v[130:133], v[210:213], v[170:173], v[130:133]
	v_mfma_f32_16x16x32_bf16 v[118:121], v[202:205], v[178:181], v[118:121]
	v_mfma_f32_16x16x32_bf16 v[114:117], v[210:213], v[178:181], v[114:117]
	v_mfma_f32_16x16x32_bf16 v[90:93], v[202:205], v[186:189], v[90:93]
	v_mfma_f32_16x16x32_bf16 v[82:85], v[210:213], v[186:189], v[82:85]
	v_mfma_f32_16x16x32_bf16 v[70:73], v[202:205], v[194:197], v[70:73]
	v_mfma_f32_16x16x32_bf16 v[66:69], v[210:213], v[194:197], v[66:69]
	s_setprio 0
	s_mov_b32 m0, s34
	v_lshl_add_u64 v[214:215], v[228:229], 0, s[74:75]
	s_barrier
	ds_read_b128 v[162:165], v168 offset:49152
	ds_read_b128 v[170:173], v168 offset:50176
	ds_read_b128 v[174:177], v168 offset:51200
	ds_read_b128 v[178:181], v168 offset:52224
	ds_read_b128 v[182:185], v168 offset:53248
	ds_read_b128 v[186:189], v168 offset:54272
	ds_read_b128 v[190:193], v168 offset:55296
	ds_read_b128 v[194:197], v168 offset:56320
	global_load_lds_dwordx4 v[214:215], off
	v_lshl_add_u64 v[214:215], v[230:231], 0, s[74:75]
	s_mov_b32 m0, s35
	s_nop 0
	global_load_lds_dwordx4 v[214:215], off
	s_barrier
	s_waitcnt lgkmcnt(0)
	s_setprio 1
	s_waitcnt lgkmcnt(0)
	v_mfma_f32_16x16x32_bf16 v[62:65], v[86:89], v[162:165], v[62:65]
	v_mfma_f32_16x16x32_bf16 v[58:61], v[98:101], v[162:165], v[58:61]
	v_mfma_f32_16x16x32_bf16 v[46:49], v[86:89], v[174:177], v[46:49]
	v_mfma_f32_16x16x32_bf16 v[42:45], v[98:101], v[174:177], v[42:45]
	v_mfma_f32_16x16x32_bf16 v[30:33], v[86:89], v[182:185], v[30:33]
	v_mfma_f32_16x16x32_bf16 v[26:29], v[98:101], v[182:185], v[26:29]
	v_mfma_f32_16x16x32_bf16 v[14:17], v[86:89], v[190:193], v[14:17]
	v_mfma_f32_16x16x32_bf16 v[10:13], v[98:101], v[190:193], v[10:13]
	v_mfma_f32_16x16x32_bf16 v[62:65], v[94:97], v[170:173], v[62:65]
	v_mfma_f32_16x16x32_bf16 v[58:61], v[106:109], v[170:173], v[58:61]
	v_mfma_f32_16x16x32_bf16 v[46:49], v[94:97], v[178:181], v[46:49]
	v_mfma_f32_16x16x32_bf16 v[42:45], v[106:109], v[178:181], v[42:45]
	v_mfma_f32_16x16x32_bf16 v[30:33], v[94:97], v[186:189], v[30:33]
	v_mfma_f32_16x16x32_bf16 v[26:29], v[106:109], v[186:189], v[26:29]
	v_mfma_f32_16x16x32_bf16 v[14:17], v[94:97], v[194:197], v[14:17]
	v_mfma_f32_16x16x32_bf16 v[10:13], v[106:109], v[194:197], v[10:13]
	s_setprio 0
	s_barrier
	s_add_u32 s20, s20, 0x10080
	s_addc_u32 s21, s21, 0
	s_add_i32 s22, s22, s26
	s_mov_b32 m0, s22
	s_nop 0
	global_load_lds_dwordx4 v154, s[20:21]
	s_add_i32 m0, s22, 0x2000
	s_nop 0
	global_load_lds_dwordx4 v142, s[20:21]
	s_waitcnt vmcnt(6)
	s_barrier
	s_setprio 1
	v_mfma_f32_16x16x32_bf16 v[54:57], v[198:201], v[162:165], v[54:57]
	v_mfma_f32_16x16x32_bf16 v[50:53], v[206:209], v[162:165], v[50:53]
	v_mfma_f32_16x16x32_bf16 v[38:41], v[198:201], v[174:177], v[38:41]
	v_mfma_f32_16x16x32_bf16 v[34:37], v[206:209], v[174:177], v[34:37]
	v_mfma_f32_16x16x32_bf16 v[22:25], v[198:201], v[182:185], v[22:25]
	v_mfma_f32_16x16x32_bf16 v[18:21], v[206:209], v[182:185], v[18:21]
	v_mfma_f32_16x16x32_bf16 v[6:9], v[198:201], v[190:193], v[6:9]
	v_mfma_f32_16x16x32_bf16 v[2:5], v[206:209], v[190:193], v[2:5]
	v_mfma_f32_16x16x32_bf16 v[54:57], v[202:205], v[170:173], v[54:57]
	v_mfma_f32_16x16x32_bf16 v[50:53], v[210:213], v[170:173], v[50:53]
	v_mfma_f32_16x16x32_bf16 v[38:41], v[202:205], v[178:181], v[38:41]
	v_mfma_f32_16x16x32_bf16 v[34:37], v[210:213], v[178:181], v[34:37]
	v_mfma_f32_16x16x32_bf16 v[22:25], v[202:205], v[186:189], v[22:25]
	v_mfma_f32_16x16x32_bf16 v[18:21], v[210:213], v[186:189], v[18:21]
	v_mfma_f32_16x16x32_bf16 v[6:9], v[202:205], v[194:197], v[6:9]
	v_mfma_f32_16x16x32_bf16 v[2:5], v[210:213], v[194:197], v[2:5]
	s_setprio 0
	s_add_u32 s6, s6, 0x100
	s_addc_u32 s7, s7, 0
	s_add_u32 s42, s42, 0x100
	s_addc_u32 s43, s43, 0
	s_cmp_ge_i32 s44, s31
	s_mov_b32 s20, s44
	s_cbranch_scc0 .LBB0_410
	s_barrier
	v_mov_b32_e32 v203, v216

.LBB0_987:
	s_add_i32 s31, s3, -2
	s_add_u32 s34, s10, 0x100
	v_mov_b32_e32 v2, 0
	s_mov_b32 s41, s37
	s_addc_u32 s35, s11, 0
	s_mov_b32 s12, 0
	v_mov_b32_e32 v3, v2
	v_mov_b32_e32 v4, v2
	v_mov_b32_e32 v5, v2
	v_mov_b32_e32 v6, v2
	v_mov_b32_e32 v7, v2
	v_mov_b32_e32 v8, v2
	v_mov_b32_e32 v9, v2
	v_mov_b32_e32 v18, v2
	v_mov_b32_e32 v19, v2
	v_mov_b32_e32 v20, v2
	v_mov_b32_e32 v21, v2
	v_mov_b32_e32 v22, v2
	v_mov_b32_e32 v23, v2
	v_mov_b32_e32 v24, v2
	v_mov_b32_e32 v25, v2
	v_mov_b32_e32 v34, v2
	v_mov_b32_e32 v35, v2
	v_mov_b32_e32 v36, v2
	v_mov_b32_e32 v37, v2
	v_mov_b32_e32 v38, v2
	v_mov_b32_e32 v39, v2
	v_mov_b32_e32 v40, v2
	v_mov_b32_e32 v41, v2
	v_mov_b32_e32 v50, v2
	v_mov_b32_e32 v51, v2
	v_mov_b32_e32 v52, v2
	v_mov_b32_e32 v53, v2
	v_mov_b32_e32 v54, v2
	v_mov_b32_e32 v55, v2
	v_mov_b32_e32 v56, v2
	v_mov_b32_e32 v57, v2
	v_mov_b32_e32 v10, v2
	v_mov_b32_e32 v11, v2
	v_mov_b32_e32 v12, v2
	v_mov_b32_e32 v13, v2
	v_mov_b32_e32 v14, v2
	v_mov_b32_e32 v15, v2
	v_mov_b32_e32 v16, v2
	v_mov_b32_e32 v17, v2
	v_mov_b32_e32 v26, v2
	v_mov_b32_e32 v27, v2
	v_mov_b32_e32 v28, v2
	v_mov_b32_e32 v29, v2
	v_mov_b32_e32 v30, v2
	v_mov_b32_e32 v31, v2
	v_mov_b32_e32 v32, v2
	v_mov_b32_e32 v33, v2
	v_mov_b32_e32 v42, v2
	v_mov_b32_e32 v43, v2
	v_mov_b32_e32 v44, v2
	v_mov_b32_e32 v45, v2
	v_mov_b32_e32 v46, v2
	v_mov_b32_e32 v47, v2
	v_mov_b32_e32 v48, v2
	v_mov_b32_e32 v49, v2
	v_mov_b32_e32 v58, v2
	v_mov_b32_e32 v59, v2
	v_mov_b32_e32 v60, v2
	v_mov_b32_e32 v61, v2
	v_mov_b32_e32 v62, v2
	v_mov_b32_e32 v63, v2
	v_mov_b32_e32 v64, v2
	v_mov_b32_e32 v65, v2
	v_mov_b32_e32 v70, v2
	v_mov_b32_e32 v71, v2
	v_mov_b32_e32 v72, v2
	v_mov_b32_e32 v73, v2
	v_mov_b32_e32 v74, v2
	v_mov_b32_e32 v75, v2
	v_mov_b32_e32 v76, v2
	v_mov_b32_e32 v77, v2
	v_mov_b32_e32 v94, v2
	v_mov_b32_e32 v95, v2
	v_mov_b32_e32 v96, v2
	v_mov_b32_e32 v97, v2
	v_mov_b32_e32 v98, v2
	v_mov_b32_e32 v99, v2
	v_mov_b32_e32 v100, v2
	v_mov_b32_e32 v101, v2
	v_mov_b32_e32 v118, v2
	v_mov_b32_e32 v119, v2
	v_mov_b32_e32 v120, v2
	v_mov_b32_e32 v121, v2
	v_mov_b32_e32 v122, v2
	v_mov_b32_e32 v123, v2
	v_mov_b32_e32 v124, v2
	v_mov_b32_e32 v125, v2
	v_mov_b32_e32 v148, v2
	v_mov_b32_e32 v149, v2
	v_mov_b32_e32 v150, v2
	v_mov_b32_e32 v151, v2
	v_mov_b32_e32 v152, v2
	v_mov_b32_e32 v153, v2
	v_mov_b32_e32 v154, v2
	v_mov_b32_e32 v155, v2
	v_mov_b32_e32 v82, v2
	v_mov_b32_e32 v83, v2
	v_mov_b32_e32 v84, v2
	v_mov_b32_e32 v85, v2
	v_mov_b32_e32 v86, v2
	v_mov_b32_e32 v87, v2
	v_mov_b32_e32 v88, v2
	v_mov_b32_e32 v89, v2
	v_mov_b32_e32 v106, v2
	v_mov_b32_e32 v107, v2
	v_mov_b32_e32 v108, v2
	v_mov_b32_e32 v109, v2
	v_mov_b32_e32 v110, v2
	v_mov_b32_e32 v111, v2
	v_mov_b32_e32 v112, v2
	v_mov_b32_e32 v113, v2
	v_mov_b32_e32 v130, v2
	v_mov_b32_e32 v131, v2
	v_mov_b32_e32 v132, v2
	v_mov_b32_e32 v133, v2
	v_mov_b32_e32 v134, v2
	v_mov_b32_e32 v135, v2
	v_mov_b32_e32 v136, v2
	v_mov_b32_e32 v137, v2
	v_mov_b32_e32 v168, v2
	v_mov_b32_e32 v169, v2
	v_mov_b32_e32 v170, v2
	v_mov_b32_e32 v171, v2
	v_mov_b32_e32 v172, v2
	v_mov_b32_e32 v173, v2
	v_mov_b32_e32 v174, v2
	v_mov_b32_e32 v175, v2
	s_mov_b64 s[42:43], 0x80
	s_branch .Lrot_2

.Lrot_2:
	s_add_i32 s36, s12, 2
	s_add_u32 s10, s0, 0x100
	s_addc_u32 s11, s1, 0
	s_add_i32 s37, 0, 0x10000
	v_add_u32_e32 v102, s37, v1
	ds_read_b128 v[66:69], v102
	ds_read_b128 v[78:81], v102 offset:1024
	ds_read_b128 v[90:93], v102 offset:2048
	ds_read_b128 v[102:105], v102 offset:3072
	s_cmp_eq_u32 s31, s12
	s_cselect_b32 s12, s4, s34
	s_cselect_b32 s15, s9, s11
	s_cselect_b32 s14, s8, s10
	s_cselect_b32 s13, s5, s35
	v_lshl_add_u64 v[184:185], s[0:1], 0, v[210:211]
	s_add_i32 m0, s20, 0xc000
	ds_read_b128 v[114:117], v226
	ds_read_b128 v[126:129], v226 offset:1024
	ds_read_b128 v[138:141], v226 offset:2048
	ds_read_b128 v[156:159], v226 offset:3072
	ds_read_b128 v[160:163], v226 offset:4096
	ds_read_b128 v[164:167], v226 offset:5120
	ds_read_b128 v[176:179], v226 offset:6144
	ds_read_b128 v[180:183], v226 offset:7168
	global_load_lds_dwordx4 v[184:185], off
	v_lshl_add_u64 v[184:185], s[0:1], 0, v[212:213]
	s_add_i32 m0, s20, 0xe000
	s_nop 0
	global_load_lds_dwordx4 v[184:185], off
	s_waitcnt lgkmcnt(8)
	s_barrier
	s_waitcnt lgkmcnt(0)
	s_setprio 1
	s_waitcnt lgkmcnt(0)
	v_mfma_f32_16x16x32_bf16 v[172:175], v[66:69], v[114:117], v[172:175]
	v_mfma_f32_16x16x32_bf16 v[168:171], v[90:93], v[114:117], v[168:171]
	v_mfma_f32_16x16x32_bf16 v[134:137], v[66:69], v[138:141], v[134:137]
	v_mfma_f32_16x16x32_bf16 v[130:133], v[90:93], v[138:141], v[130:133]
	v_mfma_f32_16x16x32_bf16 v[110:113], v[66:69], v[160:163], v[110:113]
	v_mfma_f32_16x16x32_bf16 v[106:109], v[90:93], v[160:163], v[106:109]
	v_mfma_f32_16x16x32_bf16 v[86:89], v[66:69], v[176:179], v[86:89]
	v_mfma_f32_16x16x32_bf16 v[82:85], v[90:93], v[176:179], v[82:85]
	v_mfma_f32_16x16x32_bf16 v[172:175], v[78:81], v[126:129], v[172:175]
	v_mfma_f32_16x16x32_bf16 v[168:171], v[102:105], v[126:129], v[168:171]
	v_mfma_f32_16x16x32_bf16 v[134:137], v[78:81], v[156:159], v[134:137]
	v_mfma_f32_16x16x32_bf16 v[130:133], v[102:105], v[156:159], v[130:133]
	v_mfma_f32_16x16x32_bf16 v[110:113], v[78:81], v[164:167], v[110:113]
	v_mfma_f32_16x16x32_bf16 v[106:109], v[102:105], v[164:167], v[106:109]
	v_mfma_f32_16x16x32_bf16 v[86:89], v[78:81], v[180:183], v[86:89]
	v_mfma_f32_16x16x32_bf16 v[82:85], v[102:105], v[180:183], v[82:85]
	s_setprio 0
	s_barrier
	s_add_i32 s38, 0, 0x14000
	s_add_i32 s0, s37, s19
	v_add_u32_e32 v196, s38, v1
	v_lshl_add_u64 v[234:235], s[12:13], 0, v[202:203]
	s_mov_b32 m0, s0
	ds_read_b128 v[184:187], v196
	ds_read_b128 v[188:191], v196 offset:1024
	ds_read_b128 v[192:195], v196 offset:2048
	ds_read_b128 v[196:199], v196 offset:3072
	global_load_lds_dwordx4 v[234:235], off
	v_lshl_add_u64 v[236:237], s[12:13], 0, v[142:143]
	s_add_i32 m0, s0, 0x2000
	s_nop 0
	global_load_lds_dwordx4 v[236:237], off
	s_barrier
	s_waitcnt lgkmcnt(0)
	s_setprio 1
	s_waitcnt lgkmcnt(0)
	v_mfma_f32_16x16x32_bf16 v[152:155], v[184:187], v[114:117], v[152:155]
	v_mfma_f32_16x16x32_bf16 v[122:125], v[184:187], v[138:141], v[122:125]
	v_mfma_f32_16x16x32_bf16 v[118:121], v[192:195], v[138:141], v[118:121]
	v_mfma_f32_16x16x32_bf16 v[98:101], v[184:187], v[160:163], v[98:101]
	v_mfma_f32_16x16x32_bf16 v[94:97], v[192:195], v[160:163], v[94:97]
	v_mfma_f32_16x16x32_bf16 v[74:77], v[184:187], v[176:179], v[74:77]
	v_mfma_f32_16x16x32_bf16 v[70:73], v[192:195], v[176:179], v[70:73]
	v_mfma_f32_16x16x32_bf16 v[152:155], v[188:191], v[126:129], v[152:155]
	v_mfma_f32_16x16x32_bf16 v[114:117], v[192:195], v[114:117], v[148:151]
	v_mfma_f32_16x16x32_bf16 v[122:125], v[188:191], v[156:159], v[122:125]
	v_mfma_f32_16x16x32_bf16 v[118:121], v[196:199], v[156:159], v[118:121]
	v_mfma_f32_16x16x32_bf16 v[98:101], v[188:191], v[164:167], v[98:101]
	v_mfma_f32_16x16x32_bf16 v[94:97], v[196:199], v[164:167], v[94:97]
	v_mfma_f32_16x16x32_bf16 v[74:77], v[188:191], v[180:183], v[74:77]
	v_mfma_f32_16x16x32_bf16 v[70:73], v[196:199], v[180:183], v[70:73]
	v_mfma_f32_16x16x32_bf16 v[114:117], v[196:199], v[126:129], v[114:117]
	s_setprio 0
	s_mov_b32 m0, s20
	v_lshl_add_u64 v[238:239], s[14:15], 0, v[204:205]
	s_barrier
	ds_read_b128 v[126:129], v226 offset:16384
	ds_read_b128 v[138:141], v226 offset:17408
	ds_read_b128 v[148:151], v226 offset:18432
	ds_read_b128 v[156:159], v226 offset:19456
	ds_read_b128 v[160:163], v226 offset:20480
	ds_read_b128 v[164:167], v226 offset:21504
	ds_read_b128 v[176:179], v226 offset:22528
	ds_read_b128 v[180:183], v226 offset:23552
	global_load_lds_dwordx4 v[238:239], off
	v_lshl_add_u64 v[240:241], s[14:15], 0, v[200:201]
	s_mov_b32 m0, s21
	s_nop 0
	global_load_lds_dwordx4 v[240:241], off
	s_barrier
	s_waitcnt lgkmcnt(0)
	s_setprio 1
	s_waitcnt lgkmcnt(0)
	v_mfma_f32_16x16x32_bf16 v[62:65], v[66:69], v[126:129], v[62:65]
	v_mfma_f32_16x16x32_bf16 v[58:61], v[90:93], v[126:129], v[58:61]
	v_mfma_f32_16x16x32_bf16 v[46:49], v[66:69], v[148:151], v[46:49]
	v_mfma_f32_16x16x32_bf16 v[42:45], v[90:93], v[148:151], v[42:45]
	v_mfma_f32_16x16x32_bf16 v[30:33], v[66:69], v[160:163], v[30:33]
	v_mfma_f32_16x16x32_bf16 v[26:29], v[90:93], v[160:163], v[26:29]
	v_mfma_f32_16x16x32_bf16 v[14:17], v[66:69], v[176:179], v[14:17]
	v_mfma_f32_16x16x32_bf16 v[10:13], v[90:93], v[176:179], v[10:13]
	v_mfma_f32_16x16x32_bf16 v[62:65], v[78:81], v[138:141], v[62:65]
	v_mfma_f32_16x16x32_bf16 v[58:61], v[102:105], v[138:141], v[58:61]
	v_mfma_f32_16x16x32_bf16 v[46:49], v[78:81], v[156:159], v[46:49]
	v_mfma_f32_16x16x32_bf16 v[42:45], v[102:105], v[156:159], v[42:45]
	v_mfma_f32_16x16x32_bf16 v[30:33], v[78:81], v[164:167], v[30:33]
	v_mfma_f32_16x16x32_bf16 v[26:29], v[102:105], v[164:167], v[26:29]
	v_mfma_f32_16x16x32_bf16 v[14:17], v[78:81], v[180:183], v[14:17]
	v_mfma_f32_16x16x32_bf16 v[10:13], v[102:105], v[180:183], v[10:13]
	s_setprio 0
	s_barrier
	s_add_u32 s0, s12, 0xd0000
	s_addc_u32 s1, s13, 0
	s_add_i32 s37, s38, s19
	s_mov_b32 m0, s37
	s_nop 0
	global_load_lds_dwordx4 v202, s[0:1]
	s_add_i32 m0, s37, 0x2000
	s_nop 0
	global_load_lds_dwordx4 v142, s[0:1]
	s_waitcnt vmcnt(6)
	s_barrier
	s_setprio 1
	v_mfma_f32_16x16x32_bf16 v[54:57], v[184:187], v[126:129], v[54:57]
	v_mfma_f32_16x16x32_bf16 v[50:53], v[192:195], v[126:129], v[50:53]
	v_mfma_f32_16x16x32_bf16 v[38:41], v[184:187], v[148:151], v[38:41]
	v_mfma_f32_16x16x32_bf16 v[34:37], v[192:195], v[148:151], v[34:37]
	v_mfma_f32_16x16x32_bf16 v[22:25], v[184:187], v[160:163], v[22:25]
	v_mfma_f32_16x16x32_bf16 v[18:21], v[192:195], v[160:163], v[18:21]
	v_mfma_f32_16x16x32_bf16 v[6:9], v[184:187], v[176:179], v[6:9]
	v_mfma_f32_16x16x32_bf16 v[2:5], v[192:195], v[176:179], v[2:5]
	v_mfma_f32_16x16x32_bf16 v[54:57], v[188:191], v[138:141], v[54:57]
	v_mfma_f32_16x16x32_bf16 v[50:53], v[196:199], v[138:141], v[50:53]
	v_mfma_f32_16x16x32_bf16 v[38:41], v[188:191], v[156:159], v[38:41]
	v_mfma_f32_16x16x32_bf16 v[34:37], v[196:199], v[156:159], v[34:37]
	v_mfma_f32_16x16x32_bf16 v[22:25], v[188:191], v[164:167], v[22:25]
	v_mfma_f32_16x16x32_bf16 v[18:21], v[196:199], v[164:167], v[18:21]
	v_mfma_f32_16x16x32_bf16 v[6:9], v[188:191], v[180:183], v[6:9]
	v_mfma_f32_16x16x32_bf16 v[2:5], v[196:199], v[180:183], v[2:5]
	s_setprio 0
	s_add_i32 s37, 0, 0x18000
	v_add_u32_e32 v102, s37, v1
	s_barrier
	ds_read_b128 v[66:69], v102
	ds_read_b128 v[78:81], v102 offset:1024
	ds_read_b128 v[90:93], v102 offset:2048
	ds_read_b128 v[102:105], v102 offset:3072
	s_add_u32 s0, s14, 0xd0000
	s_addc_u32 s1, s15, 0
	s_mov_b32 m0, s22
	ds_read_b128 v[126:129], v226 offset:32768
	ds_read_b128 v[138:141], v226 offset:33792
	ds_read_b128 v[156:159], v226 offset:34816
	ds_read_b128 v[160:163], v226 offset:35840
	ds_read_b128 v[164:167], v226 offset:36864
	ds_read_b128 v[176:179], v226 offset:37888
	ds_read_b128 v[180:183], v226 offset:38912
	ds_read_b128 v[184:187], v226 offset:39936
	global_load_lds_dwordx4 v204, s[0:1]
	s_mov_b32 m0, s23
	s_nop 0
	global_load_lds_dwordx4 v200, s[0:1]
	s_waitcnt lgkmcnt(8)
	s_barrier
	s_waitcnt lgkmcnt(0)
	s_setprio 1
	s_waitcnt lgkmcnt(0)
	v_mfma_f32_16x16x32_bf16 v[148:151], v[66:69], v[126:129], v[172:175]
	v_mfma_f32_16x16x32_bf16 v[172:175], v[78:81], v[138:141], v[148:151]
	v_mfma_f32_16x16x32_bf16 v[148:151], v[90:93], v[126:129], v[168:171]
	v_mfma_f32_16x16x32_bf16 v[134:137], v[66:69], v[156:159], v[134:137]
	v_mfma_f32_16x16x32_bf16 v[130:133], v[90:93], v[156:159], v[130:133]
	v_mfma_f32_16x16x32_bf16 v[110:113], v[66:69], v[164:167], v[110:113]
	v_mfma_f32_16x16x32_bf16 v[106:109], v[90:93], v[164:167], v[106:109]
	v_mfma_f32_16x16x32_bf16 v[86:89], v[66:69], v[180:183], v[86:89]
	v_mfma_f32_16x16x32_bf16 v[82:85], v[90:93], v[180:183], v[82:85]
	v_mfma_f32_16x16x32_bf16 v[168:171], v[102:105], v[138:141], v[148:151]
	v_mfma_f32_16x16x32_bf16 v[134:137], v[78:81], v[160:163], v[134:137]
	v_mfma_f32_16x16x32_bf16 v[130:133], v[102:105], v[160:163], v[130:133]
	v_mfma_f32_16x16x32_bf16 v[110:113], v[78:81], v[176:179], v[110:113]
	v_mfma_f32_16x16x32_bf16 v[106:109], v[102:105], v[176:179], v[106:109]
	v_mfma_f32_16x16x32_bf16 v[86:89], v[78:81], v[184:187], v[86:89]
	v_mfma_f32_16x16x32_bf16 v[82:85], v[102:105], v[184:187], v[82:85]
	s_setprio 0
	s_barrier
	s_add_i32 s14, 0, 0x1c000
	v_add_u32_e32 v148, s14, v1
	s_add_i32 s0, s37, s19
	ds_read_b128 v[188:191], v148
	ds_read_b128 v[192:195], v148 offset:1024
	ds_read_b128 v[196:199], v148 offset:2048
	ds_read_b128 v[230:233], v148 offset:3072
	v_lshl_add_u64 v[148:149], v[234:235], 0, s[42:43]
	s_mov_b32 m0, s0
	s_nop 0
	global_load_lds_dwordx4 v[148:149], off
	v_lshl_add_u64 v[148:149], v[236:237], 0, s[42:43]
	s_add_i32 m0, s0, 0x2000
	s_nop 0
	global_load_lds_dwordx4 v[148:149], off
	s_barrier
	s_waitcnt lgkmcnt(0)
	s_setprio 1
	s_waitcnt lgkmcnt(0)
	v_mfma_f32_16x16x32_bf16 v[148:151], v[188:191], v[126:129], v[152:155]
	v_mfma_f32_16x16x32_bf16 v[114:117], v[196:199], v[126:129], v[114:117]
	v_mfma_f32_16x16x32_bf16 v[152:155], v[192:195], v[138:141], v[148:151]
	v_mfma_f32_16x16x32_bf16 v[148:151], v[230:233], v[138:141], v[114:117]
	v_mfma_f32_16x16x32_bf16 v[114:117], v[188:191], v[156:159], v[122:125]
	v_mfma_f32_16x16x32_bf16 v[122:125], v[192:195], v[160:163], v[114:117]
	v_mfma_f32_16x16x32_bf16 v[114:117], v[196:199], v[156:159], v[118:121]
	v_mfma_f32_16x16x32_bf16 v[98:101], v[188:191], v[164:167], v[98:101]
	v_mfma_f32_16x16x32_bf16 v[94:97], v[196:199], v[164:167], v[94:97]
	v_mfma_f32_16x16x32_bf16 v[74:77], v[188:191], v[180:183], v[74:77]
	v_mfma_f32_16x16x32_bf16 v[70:73], v[196:199], v[180:183], v[70:73]
	v_mfma_f32_16x16x32_bf16 v[118:121], v[230:233], v[160:163], v[114:117]
	v_mfma_f32_16x16x32_bf16 v[98:101], v[192:195], v[176:179], v[98:101]
	v_mfma_f32_16x16x32_bf16 v[94:97], v[230:233], v[176:179], v[94:97]
	v_mfma_f32_16x16x32_bf16 v[74:77], v[192:195], v[184:187], v[74:77]
	v_mfma_f32_16x16x32_bf16 v[70:73], v[230:233], v[184:187], v[70:73]
	s_setprio 0
	s_mov_b32 m0, s25
	v_lshl_add_u64 v[184:185], v[238:239], 0, s[42:43]
	s_barrier
	ds_read_b128 v[114:117], v226 offset:49152
	ds_read_b128 v[126:129], v226 offset:50176
	ds_read_b128 v[138:141], v226 offset:51200
	ds_read_b128 v[156:159], v226 offset:52224
	ds_read_b128 v[160:163], v226 offset:53248
	ds_read_b128 v[164:167], v226 offset:54272
	ds_read_b128 v[176:179], v226 offset:55296
	ds_read_b128 v[180:183], v226 offset:56320
	global_load_lds_dwordx4 v[184:185], off
	v_lshl_add_u64 v[184:185], v[240:241], 0, s[42:43]
	s_mov_b32 m0, s26
	s_nop 0
	global_load_lds_dwordx4 v[184:185], off
	s_barrier
	s_waitcnt lgkmcnt(0)
	s_setprio 1
	s_waitcnt lgkmcnt(0)
	v_mfma_f32_16x16x32_bf16 v[62:65], v[66:69], v[114:117], v[62:65]
	v_mfma_f32_16x16x32_bf16 v[58:61], v[90:93], v[114:117], v[58:61]
	v_mfma_f32_16x16x32_bf16 v[46:49], v[66:69], v[138:141], v[46:49]
	v_mfma_f32_16x16x32_bf16 v[42:45], v[90:93], v[138:141], v[42:45]
	v_mfma_f32_16x16x32_bf16 v[30:33], v[66:69], v[160:163], v[30:33]
	v_mfma_f32_16x16x32_bf16 v[26:29], v[90:93], v[160:163], v[26:29]
	v_mfma_f32_16x16x32_bf16 v[14:17], v[66:69], v[176:179], v[14:17]
	v_mfma_f32_16x16x32_bf16 v[10:13], v[90:93], v[176:179], v[10:13]
	v_mfma_f32_16x16x32_bf16 v[62:65], v[78:81], v[126:129], v[62:65]
	v_mfma_f32_16x16x32_bf16 v[58:61], v[102:105], v[126:129], v[58:61]
	v_mfma_f32_16x16x32_bf16 v[46:49], v[78:81], v[156:159], v[46:49]
	v_mfma_f32_16x16x32_bf16 v[42:45], v[102:105], v[156:159], v[42:45]
	v_mfma_f32_16x16x32_bf16 v[30:33], v[78:81], v[164:167], v[30:33]
	v_mfma_f32_16x16x32_bf16 v[26:29], v[102:105], v[164:167], v[26:29]
	v_mfma_f32_16x16x32_bf16 v[14:17], v[78:81], v[180:183], v[14:17]
	v_mfma_f32_16x16x32_bf16 v[10:13], v[102:105], v[180:183], v[10:13]
	s_setprio 0
	s_barrier
	s_add_u32 s0, s12, 0xd0080
	s_addc_u32 s1, s13, 0
	s_add_i32 s12, s14, s19
	s_mov_b32 m0, s12
	s_nop 0
	global_load_lds_dwordx4 v202, s[0:1]
	s_add_i32 m0, s12, 0x2000
	s_nop 0
	global_load_lds_dwordx4 v142, s[0:1]
	s_waitcnt vmcnt(6)
	s_barrier
	s_setprio 1
	v_mfma_f32_16x16x32_bf16 v[54:57], v[188:191], v[114:117], v[54:57]
	v_mfma_f32_16x16x32_bf16 v[50:53], v[196:199], v[114:117], v[50:53]
	v_mfma_f32_16x16x32_bf16 v[38:41], v[188:191], v[138:141], v[38:41]
	v_mfma_f32_16x16x32_bf16 v[34:37], v[196:199], v[138:141], v[34:37]
	v_mfma_f32_16x16x32_bf16 v[22:25], v[188:191], v[160:163], v[22:25]
	v_mfma_f32_16x16x32_bf16 v[18:21], v[196:199], v[160:163], v[18:21]
	v_mfma_f32_16x16x32_bf16 v[6:9], v[188:191], v[176:179], v[6:9]
	v_mfma_f32_16x16x32_bf16 v[2:5], v[196:199], v[176:179], v[2:5]
	v_mfma_f32_16x16x32_bf16 v[54:57], v[192:195], v[126:129], v[54:57]
	v_mfma_f32_16x16x32_bf16 v[50:53], v[230:233], v[126:129], v[50:53]
	v_mfma_f32_16x16x32_bf16 v[38:41], v[192:195], v[156:159], v[38:41]
	v_mfma_f32_16x16x32_bf16 v[34:37], v[230:233], v[156:159], v[34:37]
	v_mfma_f32_16x16x32_bf16 v[22:25], v[192:195], v[164:167], v[22:25]
	v_mfma_f32_16x16x32_bf16 v[18:21], v[230:233], v[164:167], v[18:21]
	v_mfma_f32_16x16x32_bf16 v[6:9], v[192:195], v[180:183], v[6:9]
	v_mfma_f32_16x16x32_bf16 v[2:5], v[230:233], v[180:183], v[2:5]
	s_setprio 0
	s_add_u32 s34, s34, 0x100
	s_addc_u32 s35, s35, 0
	s_cmp_ge_i32 s36, s3
	s_mov_b64 s[0:1], s[10:11]
	s_mov_b32 s12, s36
	s_cbranch_scc0 .LBB0_988
	s_barrier
	v_readlane_b32 s38, v255, 8
	v_readlane_b32 s39, v255, 9
	v_readlane_b32 s35, v255, 10
	s_mov_b32 s37, s41
	s_branch .LBB0_993

.LBB0_1065:
	s_ashr_i32 s11, s10, 31
	s_lshl_b64 s[12:13], s[10:11], 19
	v_readlane_b32 s14, v254, 11
	v_readlane_b32 s15, v254, 12
	s_add_u32 s12, s14, s12
	s_addc_u32 s13, s15, s13
	s_ashr_i32 s9, s8, 31
	s_lshl_b64 s[14:15], s[8:9], 19
	v_mov_b64_e32 v[2:3], 0x100
	s_add_u32 s14, s20, s14
	v_cmp_lt_i64_e64 s[6:7], s[6:7], v[2:3]
	v_mov_b32_e32 v218, 0xff800000
	v_mov_b32_e32 v216, 0xffffff80
	s_addc_u32 s15, s21, s15
	s_andn2_b64 vcc, exec, s[0:1]
	s_cbranch_vccnz .Lzk_4
	s_and_b64 s[6:7], s[6:7], exec
	s_cselect_b32 s9, s13, s19
	s_cselect_b32 s11, s12, s18
	s_cselect_b32 s36, s15, s17
	s_cselect_b32 s37, s14, s16
	s_add_u32 s6, s18, 0x40080
	s_addc_u32 s7, s19, 0
	s_add_u32 s38, s16, 0x100
	v_mov_b32_e32 v2, 0
	s_addc_u32 s39, s17, 0
	s_mov_b32 s16, 0
	v_mov_b32_e32 v3, v2
	v_mov_b32_e32 v4, v2
	v_mov_b32_e32 v5, v2
	v_mov_b32_e32 v6, v2
	v_mov_b32_e32 v7, v2
	v_mov_b32_e32 v8, v2
	v_mov_b32_e32 v9, v2
	v_mov_b32_e32 v18, v2
	v_mov_b32_e32 v19, v2
	v_mov_b32_e32 v20, v2
	v_mov_b32_e32 v21, v2
	v_mov_b32_e32 v22, v2
	v_mov_b32_e32 v23, v2
	v_mov_b32_e32 v24, v2
	v_mov_b32_e32 v25, v2
	v_mov_b32_e32 v34, v2
	v_mov_b32_e32 v35, v2
	v_mov_b32_e32 v36, v2
	v_mov_b32_e32 v37, v2
	v_mov_b32_e32 v38, v2
	v_mov_b32_e32 v39, v2
	v_mov_b32_e32 v40, v2
	v_mov_b32_e32 v41, v2
	v_mov_b32_e32 v50, v2
	v_mov_b32_e32 v51, v2
	v_mov_b32_e32 v52, v2
	v_mov_b32_e32 v53, v2
	v_mov_b32_e32 v54, v2
	v_mov_b32_e32 v55, v2
	v_mov_b32_e32 v56, v2
	v_mov_b32_e32 v57, v2
	v_mov_b32_e32 v10, v2
	v_mov_b32_e32 v11, v2
	v_mov_b32_e32 v12, v2
	v_mov_b32_e32 v13, v2
	v_mov_b32_e32 v14, v2
	v_mov_b32_e32 v15, v2
	v_mov_b32_e32 v16, v2
	v_mov_b32_e32 v17, v2
	v_mov_b32_e32 v26, v2
	v_mov_b32_e32 v27, v2
	v_mov_b32_e32 v28, v2
	v_mov_b32_e32 v29, v2
	v_mov_b32_e32 v30, v2
	v_mov_b32_e32 v31, v2
	v_mov_b32_e32 v32, v2
	v_mov_b32_e32 v33, v2
	v_mov_b32_e32 v42, v2
	v_mov_b32_e32 v43, v2
	v_mov_b32_e32 v44, v2
	v_mov_b32_e32 v45, v2
	v_mov_b32_e32 v46, v2
	v_mov_b32_e32 v47, v2
	v_mov_b32_e32 v48, v2
	v_mov_b32_e32 v49, v2
	v_mov_b32_e32 v58, v2
	v_mov_b32_e32 v59, v2
	v_mov_b32_e32 v60, v2
	v_mov_b32_e32 v61, v2
	v_mov_b32_e32 v62, v2
	v_mov_b32_e32 v63, v2
	v_mov_b32_e32 v64, v2
	v_mov_b32_e32 v65, v2
	v_mov_b32_e32 v66, v2
	v_mov_b32_e32 v67, v2
	v_mov_b32_e32 v68, v2
	v_mov_b32_e32 v69, v2
	v_mov_b32_e32 v70, v2
	v_mov_b32_e32 v71, v2
	v_mov_b32_e32 v72, v2
	v_mov_b32_e32 v73, v2
	v_mov_b32_e32 v82, v2
	v_mov_b32_e32 v83, v2
	v_mov_b32_e32 v84, v2
	v_mov_b32_e32 v85, v2
	v_mov_b32_e32 v86, v2
	v_mov_b32_e32 v87, v2
	v_mov_b32_e32 v88, v2
	v_mov_b32_e32 v89, v2
	v_mov_b32_e32 v98, v2
	v_mov_b32_e32 v99, v2
	v_mov_b32_e32 v100, v2
	v_mov_b32_e32 v101, v2
	v_mov_b32_e32 v102, v2
	v_mov_b32_e32 v103, v2
	v_mov_b32_e32 v104, v2
	v_mov_b32_e32 v105, v2
	v_mov_b32_e32 v114, v2
	v_mov_b32_e32 v115, v2
	v_mov_b32_e32 v116, v2
	v_mov_b32_e32 v117, v2
	v_mov_b32_e32 v118, v2
	v_mov_b32_e32 v119, v2
	v_mov_b32_e32 v120, v2
	v_mov_b32_e32 v121, v2
	v_mov_b32_e32 v74, v2
	v_mov_b32_e32 v75, v2
	v_mov_b32_e32 v76, v2
	v_mov_b32_e32 v77, v2
	v_mov_b32_e32 v78, v2
	v_mov_b32_e32 v79, v2
	v_mov_b32_e32 v80, v2
	v_mov_b32_e32 v81, v2
	v_mov_b32_e32 v90, v2
	v_mov_b32_e32 v91, v2
	v_mov_b32_e32 v92, v2
	v_mov_b32_e32 v93, v2
	v_mov_b32_e32 v94, v2
	v_mov_b32_e32 v95, v2
	v_mov_b32_e32 v96, v2
	v_mov_b32_e32 v97, v2
	v_mov_b32_e32 v106, v2
	v_mov_b32_e32 v107, v2
	v_mov_b32_e32 v108, v2
	v_mov_b32_e32 v109, v2
	v_mov_b32_e32 v110, v2
	v_mov_b32_e32 v111, v2
	v_mov_b32_e32 v112, v2
	v_mov_b32_e32 v113, v2
	v_mov_b32_e32 v122, v2
	v_mov_b32_e32 v123, v2
	v_mov_b32_e32 v124, v2
	v_mov_b32_e32 v125, v2
	v_mov_b32_e32 v126, v2
	v_mov_b32_e32 v127, v2
	v_mov_b32_e32 v128, v2
	v_mov_b32_e32 v129, v2
	s_mov_b64 s[46:47], 0x80
	s_branch .Lrot_3

.Lrot_3:
	s_add_i32 s40, s16, 2
	s_add_u32 s17, s6, 0xfffc0080
	s_addc_u32 s18, s7, -1
	s_add_i32 s41, 0, 0x10000
	v_add_u32_e32 v148, s41, v184
	ds_read_b128 v[130:133], v148
	ds_read_b128 v[134:137], v148 offset:1024
	ds_read_b128 v[138:141], v148 offset:2048
	ds_read_b128 v[148:151], v148 offset:3072
	s_cmp_eq_u32 s30, s16
	s_cselect_b32 s16, s37, s38
	s_cselect_b32 s19, s9, s18
	s_cselect_b32 s18, s11, s17
	s_cselect_b32 s17, s36, s39
	s_add_i32 m0, s23, 0xc000
	ds_read_b128 v[152:155], v186
	ds_read_b128 v[156:159], v186 offset:1024
	ds_read_b128 v[160:163], v186 offset:2048
	ds_read_b128 v[174:177], v186 offset:3072
	ds_read_b128 v[178:181], v186 offset:4096
	ds_read_b128 v[188:191], v186 offset:5120
	ds_read_b128 v[192:195], v186 offset:6144
	ds_read_b128 v[196:199], v186 offset:7168
	global_load_lds_dwordx4 v170, s[6:7]
	s_add_i32 m0, s23, 0xe000
	s_nop 0
	global_load_lds_dwordx4 v172, s[6:7]
	s_waitcnt lgkmcnt(8)
	s_barrier
	s_waitcnt lgkmcnt(0)
	s_setprio 1
	s_waitcnt lgkmcnt(0)
	v_mfma_f32_16x16x32_bf16 v[126:129], v[130:133], v[152:155], v[126:129]
	v_mfma_f32_16x16x32_bf16 v[122:125], v[138:141], v[152:155], v[122:125]
	v_mfma_f32_16x16x32_bf16 v[110:113], v[130:133], v[160:163], v[110:113]
	v_mfma_f32_16x16x32_bf16 v[106:109], v[138:141], v[160:163], v[106:109]
	v_mfma_f32_16x16x32_bf16 v[94:97], v[130:133], v[178:181], v[94:97]
	v_mfma_f32_16x16x32_bf16 v[90:93], v[138:141], v[178:181], v[90:93]
	v_mfma_f32_16x16x32_bf16 v[78:81], v[130:133], v[192:195], v[78:81]
	v_mfma_f32_16x16x32_bf16 v[74:77], v[138:141], v[192:195], v[74:77]
	v_mfma_f32_16x16x32_bf16 v[126:129], v[134:137], v[156:159], v[126:129]
	v_mfma_f32_16x16x32_bf16 v[122:125], v[148:151], v[156:159], v[122:125]
	v_mfma_f32_16x16x32_bf16 v[110:113], v[134:137], v[174:177], v[110:113]
	v_mfma_f32_16x16x32_bf16 v[106:109], v[148:151], v[174:177], v[106:109]
	v_mfma_f32_16x16x32_bf16 v[94:97], v[134:137], v[188:191], v[94:97]
	v_mfma_f32_16x16x32_bf16 v[90:93], v[148:151], v[188:191], v[90:93]
	v_mfma_f32_16x16x32_bf16 v[78:81], v[134:137], v[196:199], v[78:81]
	v_mfma_f32_16x16x32_bf16 v[74:77], v[148:151], v[196:199], v[74:77]
	s_setprio 0
	s_barrier
	s_add_i32 s44, 0, 0x14000
	v_add_u32_e32 v182, s44, v184
	s_add_i32 s41, s41, s22
	ds_read_b128 v[200:203], v182
	ds_read_b128 v[204:207], v182 offset:1024
	ds_read_b128 v[208:211], v182 offset:2048
	ds_read_b128 v[212:215], v182 offset:3072
	v_lshl_add_u64 v[182:183], s[16:17], 0, v[166:167]
	s_mov_b32 m0, s41
	v_lshl_add_u64 v[226:227], s[16:17], 0, v[142:143]
	global_load_lds_dwordx4 v[182:183], off
	s_add_i32 m0, s41, 0x2000
	s_nop 0
	global_load_lds_dwordx4 v[226:227], off
	s_barrier
	s_waitcnt lgkmcnt(0)
	s_setprio 1
	s_waitcnt lgkmcnt(0)
	v_mfma_f32_16x16x32_bf16 v[118:121], v[200:203], v[152:155], v[118:121]
	v_mfma_f32_16x16x32_bf16 v[114:117], v[208:211], v[152:155], v[114:117]
	v_mfma_f32_16x16x32_bf16 v[102:105], v[200:203], v[160:163], v[102:105]
	v_mfma_f32_16x16x32_bf16 v[98:101], v[208:211], v[160:163], v[98:101]
	v_mfma_f32_16x16x32_bf16 v[86:89], v[200:203], v[178:181], v[86:89]
	v_mfma_f32_16x16x32_bf16 v[82:85], v[208:211], v[178:181], v[82:85]
	v_mfma_f32_16x16x32_bf16 v[70:73], v[200:203], v[192:195], v[70:73]
	v_mfma_f32_16x16x32_bf16 v[66:69], v[208:211], v[192:195], v[66:69]
	v_mfma_f32_16x16x32_bf16 v[118:121], v[204:207], v[156:159], v[118:121]
	v_mfma_f32_16x16x32_bf16 v[114:117], v[212:215], v[156:159], v[114:117]
	v_mfma_f32_16x16x32_bf16 v[102:105], v[204:207], v[174:177], v[102:105]
	v_mfma_f32_16x16x32_bf16 v[98:101], v[212:215], v[174:177], v[98:101]
	v_mfma_f32_16x16x32_bf16 v[86:89], v[204:207], v[188:191], v[86:89]
	v_mfma_f32_16x16x32_bf16 v[82:85], v[212:215], v[188:191], v[82:85]
	v_mfma_f32_16x16x32_bf16 v[70:73], v[204:207], v[196:199], v[70:73]
	v_mfma_f32_16x16x32_bf16 v[66:69], v[212:215], v[196:199], v[66:69]
	s_setprio 0
	s_mov_b32 m0, s23
	v_lshl_add_u64 v[228:229], s[18:19], 0, v[168:169]
	s_barrier
	ds_read_b128 v[152:155], v186 offset:16384
	ds_read_b128 v[156:159], v186 offset:17408
	ds_read_b128 v[160:163], v186 offset:18432
	ds_read_b128 v[174:177], v186 offset:19456
	ds_read_b128 v[178:181], v186 offset:20480
	ds_read_b128 v[188:191], v186 offset:21504
	ds_read_b128 v[192:195], v186 offset:22528
	ds_read_b128 v[196:199], v186 offset:23552
	global_load_lds_dwordx4 v[228:229], off
	v_lshl_add_u64 v[230:231], s[18:19], 0, v[164:165]
	s_mov_b32 m0, s24
	s_nop 0
	global_load_lds_dwordx4 v[230:231], off
	s_barrier
	s_waitcnt lgkmcnt(0)
	s_setprio 1
	s_waitcnt lgkmcnt(0)
	v_mfma_f32_16x16x32_bf16 v[62:65], v[130:133], v[152:155], v[62:65]
	v_mfma_f32_16x16x32_bf16 v[58:61], v[138:141], v[152:155], v[58:61]
	v_mfma_f32_16x16x32_bf16 v[46:49], v[130:133], v[160:163], v[46:49]
	v_mfma_f32_16x16x32_bf16 v[42:45], v[138:141], v[160:163], v[42:45]
	v_mfma_f32_16x16x32_bf16 v[30:33], v[130:133], v[178:181], v[30:33]
	v_mfma_f32_16x16x32_bf16 v[26:29], v[138:141], v[178:181], v[26:29]
	v_mfma_f32_16x16x32_bf16 v[14:17], v[130:133], v[192:195], v[14:17]
	v_mfma_f32_16x16x32_bf16 v[10:13], v[138:141], v[192:195], v[10:13]
	v_mfma_f32_16x16x32_bf16 v[62:65], v[134:137], v[156:159], v[62:65]
	v_mfma_f32_16x16x32_bf16 v[58:61], v[148:151], v[156:159], v[58:61]
	v_mfma_f32_16x16x32_bf16 v[46:49], v[134:137], v[174:177], v[46:49]
	v_mfma_f32_16x16x32_bf16 v[42:45], v[148:151], v[174:177], v[42:45]
	v_mfma_f32_16x16x32_bf16 v[30:33], v[134:137], v[188:191], v[30:33]
	v_mfma_f32_16x16x32_bf16 v[26:29], v[148:151], v[188:191], v[26:29]
	v_mfma_f32_16x16x32_bf16 v[14:17], v[134:137], v[196:199], v[14:17]
	v_mfma_f32_16x16x32_bf16 v[10:13], v[148:151], v[196:199], v[10:13]
	s_setprio 0
	s_barrier
	s_add_u32 s42, s16, 0x40000
	s_addc_u32 s43, s17, 0
	s_add_i32 s41, s44, s22
	s_mov_b32 m0, s41
	s_nop 0
	global_load_lds_dwordx4 v166, s[42:43]
	s_add_i32 m0, s41, 0x2000
	s_nop 0
	global_load_lds_dwordx4 v142, s[42:43]
	s_waitcnt vmcnt(6)
	s_barrier
	s_setprio 1
	v_mfma_f32_16x16x32_bf16 v[54:57], v[200:203], v[152:155], v[54:57]
	v_mfma_f32_16x16x32_bf16 v[50:53], v[208:211], v[152:155], v[50:53]
	v_mfma_f32_16x16x32_bf16 v[38:41], v[200:203], v[160:163], v[38:41]
	v_mfma_f32_16x16x32_bf16 v[34:37], v[208:211], v[160:163], v[34:37]
	v_mfma_f32_16x16x32_bf16 v[22:25], v[200:203], v[178:181], v[22:25]
	v_mfma_f32_16x16x32_bf16 v[18:21], v[208:211], v[178:181], v[18:21]
	v_mfma_f32_16x16x32_bf16 v[6:9], v[200:203], v[192:195], v[6:9]
	v_mfma_f32_16x16x32_bf16 v[2:5], v[208:211], v[192:195], v[2:5]
	v_mfma_f32_16x16x32_bf16 v[54:57], v[204:207], v[156:159], v[54:57]
	v_mfma_f32_16x16x32_bf16 v[50:53], v[212:215], v[156:159], v[50:53]
	v_mfma_f32_16x16x32_bf16 v[38:41], v[204:207], v[174:177], v[38:41]
	v_mfma_f32_16x16x32_bf16 v[34:37], v[212:215], v[174:177], v[34:37]
	v_mfma_f32_16x16x32_bf16 v[22:25], v[204:207], v[188:191], v[22:25]
	v_mfma_f32_16x16x32_bf16 v[18:21], v[212:215], v[188:191], v[18:21]
	v_mfma_f32_16x16x32_bf16 v[6:9], v[204:207], v[196:199], v[6:9]
	v_mfma_f32_16x16x32_bf16 v[2:5], v[212:215], v[196:199], v[2:5]
	s_setprio 0
	s_add_i32 s41, 0, 0x18000
	v_add_u32_e32 v148, s41, v184
	s_barrier
	ds_read_b128 v[130:133], v148
	ds_read_b128 v[134:137], v148 offset:1024
	ds_read_b128 v[138:141], v148 offset:2048
	ds_read_b128 v[148:151], v148 offset:3072
	s_add_u32 s18, s18, 0x40000
	s_addc_u32 s19, s19, 0
	s_mov_b32 m0, s25
	ds_read_b128 v[152:155], v186 offset:32768
	ds_read_b128 v[156:159], v186 offset:33792
	ds_read_b128 v[160:163], v186 offset:34816
	ds_read_b128 v[174:177], v186 offset:35840
	ds_read_b128 v[178:181], v186 offset:36864
	ds_read_b128 v[188:191], v186 offset:37888
	ds_read_b128 v[192:195], v186 offset:38912
	ds_read_b128 v[196:199], v186 offset:39936
	global_load_lds_dwordx4 v168, s[18:19]
	s_mov_b32 m0, s26
	s_nop 0
	global_load_lds_dwordx4 v164, s[18:19]
	s_waitcnt lgkmcnt(8)
	s_barrier
	s_waitcnt lgkmcnt(0)
	s_setprio 1
	s_waitcnt lgkmcnt(0)
	v_mfma_f32_16x16x32_bf16 v[126:129], v[130:133], v[152:155], v[126:129]
	v_mfma_f32_16x16x32_bf16 v[122:125], v[138:141], v[152:155], v[122:125]
	v_mfma_f32_16x16x32_bf16 v[110:113], v[130:133], v[160:163], v[110:113]
	v_mfma_f32_16x16x32_bf16 v[106:109], v[138:141], v[160:163], v[106:109]
	v_mfma_f32_16x16x32_bf16 v[94:97], v[130:133], v[178:181], v[94:97]
	v_mfma_f32_16x16x32_bf16 v[90:93], v[138:141], v[178:181], v[90:93]
	v_mfma_f32_16x16x32_bf16 v[78:81], v[130:133], v[192:195], v[78:81]
	v_mfma_f32_16x16x32_bf16 v[74:77], v[138:141], v[192:195], v[74:77]
	v_mfma_f32_16x16x32_bf16 v[126:129], v[134:137], v[156:159], v[126:129]
	v_mfma_f32_16x16x32_bf16 v[122:125], v[148:151], v[156:159], v[122:125]
	v_mfma_f32_16x16x32_bf16 v[110:113], v[134:137], v[174:177], v[110:113]
	v_mfma_f32_16x16x32_bf16 v[106:109], v[148:151], v[174:177], v[106:109]
	v_mfma_f32_16x16x32_bf16 v[94:97], v[134:137], v[188:191], v[94:97]
	v_mfma_f32_16x16x32_bf16 v[90:93], v[148:151], v[188:191], v[90:93]
	v_mfma_f32_16x16x32_bf16 v[78:81], v[134:137], v[196:199], v[78:81]
	v_mfma_f32_16x16x32_bf16 v[74:77], v[148:151], v[196:199], v[74:77]
	s_setprio 0
	s_barrier
	s_add_i32 s18, 0, 0x1c000
	s_add_i32 s19, s41, s22
	v_add_u32_e32 v187, s18, v184
	v_lshl_add_u64 v[182:183], v[182:183], 0, s[46:47]
	s_mov_b32 m0, s19
	ds_read_b128 v[200:203], v187
	ds_read_b128 v[204:207], v187 offset:1024
	ds_read_b128 v[208:211], v187 offset:2048
	ds_read_b128 v[212:215], v187 offset:3072
	global_load_lds_dwordx4 v[182:183], off
	v_lshl_add_u64 v[182:183], v[226:227], 0, s[46:47]
	s_add_i32 m0, s19, 0x2000
	s_nop 0
	global_load_lds_dwordx4 v[182:183], off
	s_barrier
	s_waitcnt lgkmcnt(0)
	s_setprio 1
	s_waitcnt lgkmcnt(0)
	v_mfma_f32_16x16x32_bf16 v[118:121], v[200:203], v[152:155], v[118:121]
	v_mfma_f32_16x16x32_bf16 v[114:117], v[208:211], v[152:155], v[114:117]
	v_mfma_f32_16x16x32_bf16 v[102:105], v[200:203], v[160:163], v[102:105]
	v_mfma_f32_16x16x32_bf16 v[98:101], v[208:211], v[160:163], v[98:101]
	v_mfma_f32_16x16x32_bf16 v[86:89], v[200:203], v[178:181], v[86:89]
	v_mfma_f32_16x16x32_bf16 v[82:85], v[208:211], v[178:181], v[82:85]
	v_mfma_f32_16x16x32_bf16 v[70:73], v[200:203], v[192:195], v[70:73]
	v_mfma_f32_16x16x32_bf16 v[66:69], v[208:211], v[192:195], v[66:69]
	v_mfma_f32_16x16x32_bf16 v[118:121], v[204:207], v[156:159], v[118:121]
	v_mfma_f32_16x16x32_bf16 v[114:117], v[212:215], v[156:159], v[114:117]
	v_mfma_f32_16x16x32_bf16 v[102:105], v[204:207], v[174:177], v[102:105]
	v_mfma_f32_16x16x32_bf16 v[98:101], v[212:215], v[174:177], v[98:101]
	v_mfma_f32_16x16x32_bf16 v[86:89], v[204:207], v[188:191], v[86:89]
	v_mfma_f32_16x16x32_bf16 v[82:85], v[212:215], v[188:191], v[82:85]
	v_mfma_f32_16x16x32_bf16 v[70:73], v[204:207], v[196:199], v[70:73]
	v_mfma_f32_16x16x32_bf16 v[66:69], v[212:215], v[196:199], v[66:69]
	s_setprio 0
	s_mov_b32 m0, s28
	v_lshl_add_u64 v[182:183], v[228:229], 0, s[46:47]
	s_barrier
	ds_read_b128 v[152:155], v186 offset:49152
	ds_read_b128 v[156:159], v186 offset:50176
	ds_read_b128 v[160:163], v186 offset:51200
	ds_read_b128 v[174:177], v186 offset:52224
	ds_read_b128 v[178:181], v186 offset:53248
	ds_read_b128 v[188:191], v186 offset:54272
	ds_read_b128 v[192:195], v186 offset:55296
	ds_read_b128 v[196:199], v186 offset:56320
	global_load_lds_dwordx4 v[182:183], off
	v_lshl_add_u64 v[182:183], v[230:231], 0, s[46:47]
	s_mov_b32 m0, s29
	s_nop 0
	global_load_lds_dwordx4 v[182:183], off
	s_barrier
	s_waitcnt lgkmcnt(0)
	s_setprio 1
	s_waitcnt lgkmcnt(0)
	v_mfma_f32_16x16x32_bf16 v[62:65], v[130:133], v[152:155], v[62:65]
	v_mfma_f32_16x16x32_bf16 v[58:61], v[138:141], v[152:155], v[58:61]
	v_mfma_f32_16x16x32_bf16 v[46:49], v[130:133], v[160:163], v[46:49]
	v_mfma_f32_16x16x32_bf16 v[42:45], v[138:141], v[160:163], v[42:45]
	v_mfma_f32_16x16x32_bf16 v[30:33], v[130:133], v[178:181], v[30:33]
	v_mfma_f32_16x16x32_bf16 v[26:29], v[138:141], v[178:181], v[26:29]
	v_mfma_f32_16x16x32_bf16 v[14:17], v[130:133], v[192:195], v[14:17]
	v_mfma_f32_16x16x32_bf16 v[10:13], v[138:141], v[192:195], v[10:13]
	v_mfma_f32_16x16x32_bf16 v[62:65], v[134:137], v[156:159], v[62:65]
	v_mfma_f32_16x16x32_bf16 v[58:61], v[148:151], v[156:159], v[58:61]
	v_mfma_f32_16x16x32_bf16 v[46:49], v[134:137], v[174:177], v[46:49]
	v_mfma_f32_16x16x32_bf16 v[42:45], v[148:151], v[174:177], v[42:45]
	v_mfma_f32_16x16x32_bf16 v[30:33], v[134:137], v[188:191], v[30:33]
	v_mfma_f32_16x16x32_bf16 v[26:29], v[148:151], v[188:191], v[26:29]
	v_mfma_f32_16x16x32_bf16 v[14:17], v[134:137], v[196:199], v[14:17]
	v_mfma_f32_16x16x32_bf16 v[10:13], v[148:151], v[196:199], v[10:13]
	s_setprio 0
	s_barrier
	s_add_u32 s16, s16, 0x40080
	s_addc_u32 s17, s17, 0
	s_add_i32 s18, s18, s22
	s_mov_b32 m0, s18
	s_nop 0
	global_load_lds_dwordx4 v166, s[16:17]
	s_add_i32 m0, s18, 0x2000
	s_nop 0
	global_load_lds_dwordx4 v142, s[16:17]
	s_waitcnt vmcnt(6)
	s_barrier
	s_setprio 1
	v_mfma_f32_16x16x32_bf16 v[54:57], v[200:203], v[152:155], v[54:57]
	v_mfma_f32_16x16x32_bf16 v[50:53], v[208:211], v[152:155], v[50:53]
	v_mfma_f32_16x16x32_bf16 v[38:41], v[200:203], v[160:163], v[38:41]
	v_mfma_f32_16x16x32_bf16 v[34:37], v[208:211], v[160:163], v[34:37]
	v_mfma_f32_16x16x32_bf16 v[22:25], v[200:203], v[178:181], v[22:25]
	v_mfma_f32_16x16x32_bf16 v[18:21], v[208:211], v[178:181], v[18:21]
	v_mfma_f32_16x16x32_bf16 v[6:9], v[200:203], v[192:195], v[6:9]
	v_mfma_f32_16x16x32_bf16 v[2:5], v[208:211], v[192:195], v[2:5]
	v_mfma_f32_16x16x32_bf16 v[54:57], v[204:207], v[156:159], v[54:57]
	v_mfma_f32_16x16x32_bf16 v[50:53], v[212:215], v[156:159], v[50:53]
	v_mfma_f32_16x16x32_bf16 v[38:41], v[204:207], v[174:177], v[38:41]
	v_mfma_f32_16x16x32_bf16 v[34:37], v[212:215], v[174:177], v[34:37]
	v_mfma_f32_16x16x32_bf16 v[22:25], v[204:207], v[188:191], v[22:25]
	v_mfma_f32_16x16x32_bf16 v[18:21], v[212:215], v[188:191], v[18:21]
	v_mfma_f32_16x16x32_bf16 v[6:9], v[204:207], v[196:199], v[6:9]
	v_mfma_f32_16x16x32_bf16 v[2:5], v[212:215], v[196:199], v[2:5]
	s_setprio 0
	s_add_u32 s6, s6, 0x100
	s_addc_u32 s7, s7, 0
	s_add_u32 s38, s38, 0x100
	s_addc_u32 s39, s39, 0
	s_cmp_ge_i32 s40, s27
	s_mov_b32 s16, s40
	s_cbranch_scc0 .LBB0_1067
	s_barrier
	v_readlane_b32 s38, v255, 8
	s_mov_b32 s37, s45
	v_readlane_b32 s39, v255, 9
	s_branch .LBB0_1058

.LBB0_1279:
	s_ashr_i32 s5, s4, 31
	s_lshl_b64 s[10:11], s[4:5], 18
	s_add_u32 s10, s50, s10
	s_addc_u32 s11, s51, s11
	s_ashr_i32 s7, s6, 31
	s_lshl_b64 s[12:13], s[6:7], 18
	s_add_u32 s12, s20, s12
	s_addc_u32 s13, s21, s13
	s_andn2_b64 vcc, exec, s[0:1]
	s_cbranch_vccnz .Lzk_5
	s_and_b64 s[18:19], s[18:19], exec
	s_cselect_b32 s5, s11, s15
	s_cselect_b32 s7, s10, s14
	s_cselect_b32 s36, s13, s17
	s_cselect_b32 s37, s12, s16
	s_add_u32 s14, s14, 0x20080
	s_addc_u32 s15, s15, 0
	s_add_u32 s38, s16, 0x100
	v_mov_b32_e32 v18, 0
	v_mov_b32_e32 v218, 0xff800000
	v_mov_b32_e32 v214, 0xffffff80
	s_addc_u32 s39, s17, 0
	s_mov_b32 s16, 0
	v_mov_b32_e32 v19, v18
	v_mov_b32_e32 v20, v18
	v_mov_b32_e32 v21, v18
	v_mov_b32_e32 v26, v18
	v_mov_b32_e32 v27, v18
	v_mov_b32_e32 v28, v18
	v_mov_b32_e32 v29, v18
	v_mov_b32_e32 v34, v18
	v_mov_b32_e32 v35, v18
	v_mov_b32_e32 v36, v18
	v_mov_b32_e32 v37, v18
	v_mov_b32_e32 v42, v18
	v_mov_b32_e32 v43, v18
	v_mov_b32_e32 v44, v18
	v_mov_b32_e32 v45, v18
	v_mov_b32_e32 v50, v18
	v_mov_b32_e32 v51, v18
	v_mov_b32_e32 v52, v18
	v_mov_b32_e32 v53, v18
	v_mov_b32_e32 v58, v18
	v_mov_b32_e32 v59, v18
	v_mov_b32_e32 v60, v18
	v_mov_b32_e32 v61, v18
	v_mov_b32_e32 v66, v18
	v_mov_b32_e32 v67, v18
	v_mov_b32_e32 v68, v18
	v_mov_b32_e32 v69, v18
	v_mov_b32_e32 v74, v18
	v_mov_b32_e32 v75, v18
	v_mov_b32_e32 v76, v18
	v_mov_b32_e32 v77, v18
	v_mov_b32_e32 v22, v18
	v_mov_b32_e32 v23, v18
	v_mov_b32_e32 v24, v18
	v_mov_b32_e32 v25, v18
	v_mov_b32_e32 v30, v18
	v_mov_b32_e32 v31, v18
	v_mov_b32_e32 v32, v18
	v_mov_b32_e32 v33, v18
	v_mov_b32_e32 v38, v18
	v_mov_b32_e32 v39, v18
	v_mov_b32_e32 v40, v18
	v_mov_b32_e32 v41, v18
	v_mov_b32_e32 v46, v18
	v_mov_b32_e32 v47, v18
	v_mov_b32_e32 v48, v18
	v_mov_b32_e32 v49, v18
	v_mov_b32_e32 v54, v18
	v_mov_b32_e32 v55, v18
	v_mov_b32_e32 v56, v18
	v_mov_b32_e32 v57, v18
	v_mov_b32_e32 v62, v18
	v_mov_b32_e32 v63, v18
	v_mov_b32_e32 v64, v18
	v_mov_b32_e32 v65, v18
	v_mov_b32_e32 v70, v18
	v_mov_b32_e32 v71, v18
	v_mov_b32_e32 v72, v18
	v_mov_b32_e32 v73, v18
	v_mov_b32_e32 v78, v18
	v_mov_b32_e32 v79, v18
	v_mov_b32_e32 v80, v18
	v_mov_b32_e32 v81, v18
	v_mov_b32_e32 v82, v18
	v_mov_b32_e32 v83, v18
	v_mov_b32_e32 v84, v18
	v_mov_b32_e32 v85, v18
	v_mov_b32_e32 v90, v18
	v_mov_b32_e32 v91, v18
	v_mov_b32_e32 v92, v18
	v_mov_b32_e32 v93, v18
	v_mov_b32_e32 v98, v18
	v_mov_b32_e32 v99, v18
	v_mov_b32_e32 v100, v18
	v_mov_b32_e32 v101, v18
	v_mov_b32_e32 v106, v18
	v_mov_b32_e32 v107, v18
	v_mov_b32_e32 v108, v18
	v_mov_b32_e32 v109, v18
	v_mov_b32_e32 v114, v18
	v_mov_b32_e32 v115, v18
	v_mov_b32_e32 v116, v18
	v_mov_b32_e32 v117, v18
	v_mov_b32_e32 v122, v18
	v_mov_b32_e32 v123, v18
	v_mov_b32_e32 v124, v18
	v_mov_b32_e32 v125, v18
	v_mov_b32_e32 v130, v18
	v_mov_b32_e32 v131, v18
	v_mov_b32_e32 v132, v18
	v_mov_b32_e32 v133, v18
	v_mov_b32_e32 v138, v18
	v_mov_b32_e32 v139, v18
	v_mov_b32_e32 v140, v18
	v_mov_b32_e32 v141, v18
	v_mov_b32_e32 v86, v18
	v_mov_b32_e32 v87, v18
	v_mov_b32_e32 v88, v18
	v_mov_b32_e32 v89, v18
	v_mov_b32_e32 v94, v18
	v_mov_b32_e32 v95, v18
	v_mov_b32_e32 v96, v18
	v_mov_b32_e32 v97, v18
	v_mov_b32_e32 v102, v18
	v_mov_b32_e32 v103, v18
	v_mov_b32_e32 v104, v18
	v_mov_b32_e32 v105, v18
	v_mov_b32_e32 v110, v18
	v_mov_b32_e32 v111, v18
	v_mov_b32_e32 v112, v18
	v_mov_b32_e32 v113, v18
	v_mov_b32_e32 v118, v18
	v_mov_b32_e32 v119, v18
	v_mov_b32_e32 v120, v18
	v_mov_b32_e32 v121, v18
	v_mov_b32_e32 v126, v18
	v_mov_b32_e32 v127, v18
	v_mov_b32_e32 v128, v18
	v_mov_b32_e32 v129, v18
	v_mov_b32_e32 v134, v18
	v_mov_b32_e32 v135, v18
	v_mov_b32_e32 v136, v18
	v_mov_b32_e32 v137, v18
	v_mov_b32_e32 v148, v18
	v_mov_b32_e32 v149, v18
	v_mov_b32_e32 v150, v18
	v_mov_b32_e32 v151, v18
	s_mov_b64 s[46:47], 0x80
	s_branch .Lrot_4

.Lrot_4:
	s_add_i32 s40, s16, 2
	s_add_u32 s17, s14, 0xfffe0080
	s_addc_u32 s18, s15, -1
	s_add_i32 s41, 0, 0x10000
	v_add_u32_e32 v14, s41, v170
	ds_read_b128 v[2:5], v14
	ds_read_b128 v[6:9], v14 offset:1024
	ds_read_b128 v[10:13], v14 offset:2048
	ds_read_b128 v[14:17], v14 offset:3072
	s_cmp_eq_u32 s30, s16
	s_cselect_b32 s16, s37, s38
	s_cselect_b32 s19, s5, s18
	s_cselect_b32 s18, s7, s17
	s_cselect_b32 s17, s36, s39
	s_add_i32 m0, s23, 0xc000
	ds_read_b128 v[174:177], v172
	ds_read_b128 v[178:181], v172 offset:1024
	ds_read_b128 v[182:185], v172 offset:2048
	ds_read_b128 v[186:189], v172 offset:3072
	ds_read_b128 v[190:193], v172 offset:4096
	ds_read_b128 v[194:197], v172 offset:5120
	ds_read_b128 v[198:201], v172 offset:6144
	ds_read_b128 v[202:205], v172 offset:7168
	global_load_lds_dwordx4 v158, s[14:15]
	s_add_i32 m0, s23, 0xe000
	s_nop 0
	global_load_lds_dwordx4 v160, s[14:15]
	s_waitcnt lgkmcnt(8)
	s_barrier
	s_waitcnt lgkmcnt(0)
	s_setprio 1
	s_waitcnt lgkmcnt(0)
	v_mfma_scale_f32_16x16x128_f8f6f4 v[148:151], v[2:9], v[174:181], v[148:151], v219, v220 op_sel_hi:[0,0,0]
	v_mfma_scale_f32_16x16x128_f8f6f4 v[134:137], v[10:17], v[174:181], v[134:137], v219, v220 op_sel_hi:[0,0,0]
	v_mfma_scale_f32_16x16x128_f8f6f4 v[126:129], v[2:9], v[182:189], v[126:129], v219, v220 op_sel_hi:[0,0,0]
	v_mfma_scale_f32_16x16x128_f8f6f4 v[118:121], v[10:17], v[182:189], v[118:121], v219, v220 op_sel_hi:[0,0,0]
	v_mfma_scale_f32_16x16x128_f8f6f4 v[110:113], v[2:9], v[190:197], v[110:113], v219, v220 op_sel_hi:[0,0,0]
	v_mfma_scale_f32_16x16x128_f8f6f4 v[102:105], v[10:17], v[190:197], v[102:105], v219, v220 op_sel_hi:[0,0,0]
	v_mfma_scale_f32_16x16x128_f8f6f4 v[94:97], v[2:9], v[198:205], v[94:97], v219, v220 op_sel_hi:[0,0,0]
	v_mfma_scale_f32_16x16x128_f8f6f4 v[86:89], v[10:17], v[198:205], v[86:89], v219, v220 op_sel_hi:[0,0,0]
	s_setprio 0
	s_barrier
	s_add_i32 s44, 0, 0x14000
	v_add_u32_e32 v162, s44, v170
	s_add_i32 s41, s41, s22
	ds_read_b128 v[206:209], v162
	ds_read_b128 v[210:213], v162 offset:1024
	ds_read_b128 v[226:229], v162 offset:2048
	ds_read_b128 v[230:233], v162 offset:3072
	v_lshl_add_u64 v[162:163], s[16:17], 0, v[154:155]
	s_mov_b32 m0, s41
	v_lshl_add_u64 v[164:165], s[16:17], 0, v[142:143]
	global_load_lds_dwordx4 v[162:163], off
	s_add_i32 m0, s41, 0x2000
	s_nop 0
	global_load_lds_dwordx4 v[164:165], off
	s_barrier
	s_waitcnt lgkmcnt(0)
	s_setprio 1
	s_waitcnt lgkmcnt(0)
	v_mfma_scale_f32_16x16x128_f8f6f4 v[138:141], v[206:213], v[174:181], v[138:141], v219, v220 op_sel_hi:[0,0,0]
	v_mfma_scale_f32_16x16x128_f8f6f4 v[130:133], v[226:233], v[174:181], v[130:133], v219, v220 op_sel_hi:[0,0,0]
	v_mfma_scale_f32_16x16x128_f8f6f4 v[122:125], v[206:213], v[182:189], v[122:125], v219, v220 op_sel_hi:[0,0,0]
	v_mfma_scale_f32_16x16x128_f8f6f4 v[114:117], v[226:233], v[182:189], v[114:117], v219, v220 op_sel_hi:[0,0,0]
	v_mfma_scale_f32_16x16x128_f8f6f4 v[106:109], v[206:213], v[190:197], v[106:109], v219, v220 op_sel_hi:[0,0,0]
	v_mfma_scale_f32_16x16x128_f8f6f4 v[98:101], v[226:233], v[190:197], v[98:101], v219, v220 op_sel_hi:[0,0,0]
	v_mfma_scale_f32_16x16x128_f8f6f4 v[90:93], v[206:213], v[198:205], v[90:93], v219, v220 op_sel_hi:[0,0,0]
	v_mfma_scale_f32_16x16x128_f8f6f4 v[82:85], v[226:233], v[198:205], v[82:85], v219, v220 op_sel_hi:[0,0,0]
	s_setprio 0
	s_mov_b32 m0, s23
	v_lshl_add_u64 v[166:167], s[18:19], 0, v[156:157]
	s_barrier
	ds_read_b128 v[174:177], v172 offset:16384
	ds_read_b128 v[178:181], v172 offset:17408
	ds_read_b128 v[182:185], v172 offset:18432
	ds_read_b128 v[186:189], v172 offset:19456
	ds_read_b128 v[190:193], v172 offset:20480
	ds_read_b128 v[194:197], v172 offset:21504
	ds_read_b128 v[198:201], v172 offset:22528
	ds_read_b128 v[202:205], v172 offset:23552
	global_load_lds_dwordx4 v[166:167], off
	v_lshl_add_u64 v[168:169], s[18:19], 0, v[152:153]
	s_mov_b32 m0, s24
	s_nop 0
	global_load_lds_dwordx4 v[168:169], off
	s_barrier
	s_waitcnt lgkmcnt(0)
	s_setprio 1
	s_waitcnt lgkmcnt(0)
	v_mfma_scale_f32_16x16x128_f8f6f4 v[78:81], v[2:9], v[174:181], v[78:81], v219, v220 op_sel_hi:[0,0,0]
	v_mfma_scale_f32_16x16x128_f8f6f4 v[70:73], v[10:17], v[174:181], v[70:73], v219, v220 op_sel_hi:[0,0,0]
	v_mfma_scale_f32_16x16x128_f8f6f4 v[62:65], v[2:9], v[182:189], v[62:65], v219, v220 op_sel_hi:[0,0,0]
	v_mfma_scale_f32_16x16x128_f8f6f4 v[54:57], v[10:17], v[182:189], v[54:57], v219, v220 op_sel_hi:[0,0,0]
	v_mfma_scale_f32_16x16x128_f8f6f4 v[46:49], v[2:9], v[190:197], v[46:49], v219, v220 op_sel_hi:[0,0,0]
	v_mfma_scale_f32_16x16x128_f8f6f4 v[38:41], v[10:17], v[190:197], v[38:41], v219, v220 op_sel_hi:[0,0,0]
	v_mfma_scale_f32_16x16x128_f8f6f4 v[30:33], v[2:9], v[198:205], v[30:33], v219, v220 op_sel_hi:[0,0,0]
	v_mfma_scale_f32_16x16x128_f8f6f4 v[22:25], v[10:17], v[198:205], v[22:25], v219, v220 op_sel_hi:[0,0,0]
	s_setprio 0
	s_barrier
	s_add_u32 s42, s16, 0x20000
	s_addc_u32 s43, s17, 0
	s_add_i32 s41, s44, s22
	s_mov_b32 m0, s41
	s_nop 0
	global_load_lds_dwordx4 v154, s[42:43]
	s_add_i32 m0, s41, 0x2000
	s_nop 0
	global_load_lds_dwordx4 v142, s[42:43]
	s_waitcnt vmcnt(6)
	s_barrier
	s_setprio 1
	v_mfma_scale_f32_16x16x128_f8f6f4 v[74:77], v[206:213], v[174:181], v[74:77], v219, v220 op_sel_hi:[0,0,0]
	v_mfma_scale_f32_16x16x128_f8f6f4 v[66:69], v[226:233], v[174:181], v[66:69], v219, v220 op_sel_hi:[0,0,0]
	v_mfma_scale_f32_16x16x128_f8f6f4 v[58:61], v[206:213], v[182:189], v[58:61], v219, v220 op_sel_hi:[0,0,0]
	v_mfma_scale_f32_16x16x128_f8f6f4 v[50:53], v[226:233], v[182:189], v[50:53], v219, v220 op_sel_hi:[0,0,0]
	v_mfma_scale_f32_16x16x128_f8f6f4 v[42:45], v[206:213], v[190:197], v[42:45], v219, v220 op_sel_hi:[0,0,0]
	v_mfma_scale_f32_16x16x128_f8f6f4 v[34:37], v[226:233], v[190:197], v[34:37], v219, v220 op_sel_hi:[0,0,0]
	v_mfma_scale_f32_16x16x128_f8f6f4 v[26:29], v[206:213], v[198:205], v[26:29], v219, v220 op_sel_hi:[0,0,0]
	v_mfma_scale_f32_16x16x128_f8f6f4 v[18:21], v[226:233], v[198:205], v[18:21], v219, v220 op_sel_hi:[0,0,0]
	s_setprio 0
	s_add_i32 s41, 0, 0x18000
	v_add_u32_e32 v14, s41, v170
	s_barrier
	ds_read_b128 v[2:5], v14
	ds_read_b128 v[6:9], v14 offset:1024
	ds_read_b128 v[10:13], v14 offset:2048
	ds_read_b128 v[14:17], v14 offset:3072
	s_add_u32 s18, s18, 0x20000
	s_addc_u32 s19, s19, 0
	s_mov_b32 m0, s25
	ds_read_b128 v[174:177], v172 offset:32768
	ds_read_b128 v[178:181], v172 offset:33792
	ds_read_b128 v[182:185], v172 offset:34816
	ds_read_b128 v[186:189], v172 offset:35840
	ds_read_b128 v[190:193], v172 offset:36864
	ds_read_b128 v[194:197], v172 offset:37888
	ds_read_b128 v[198:201], v172 offset:38912
	ds_read_b128 v[202:205], v172 offset:39936
	global_load_lds_dwordx4 v156, s[18:19]
	s_mov_b32 m0, s26
	s_nop 0
	global_load_lds_dwordx4 v152, s[18:19]
	s_waitcnt lgkmcnt(8)
	s_barrier
	s_waitcnt lgkmcnt(0)
	s_setprio 1
	s_waitcnt lgkmcnt(0)
	v_mfma_scale_f32_16x16x128_f8f6f4 v[148:151], v[2:9], v[174:181], v[148:151], v219, v220 op_sel_hi:[0,0,0]
	v_mfma_scale_f32_16x16x128_f8f6f4 v[134:137], v[10:17], v[174:181], v[134:137], v219, v220 op_sel_hi:[0,0,0]
	v_mfma_scale_f32_16x16x128_f8f6f4 v[126:129], v[2:9], v[182:189], v[126:129], v219, v220 op_sel_hi:[0,0,0]
	v_mfma_scale_f32_16x16x128_f8f6f4 v[118:121], v[10:17], v[182:189], v[118:121], v219, v220 op_sel_hi:[0,0,0]
	v_mfma_scale_f32_16x16x128_f8f6f4 v[110:113], v[2:9], v[190:197], v[110:113], v219, v220 op_sel_hi:[0,0,0]
	v_mfma_scale_f32_16x16x128_f8f6f4 v[102:105], v[10:17], v[190:197], v[102:105], v219, v220 op_sel_hi:[0,0,0]
	v_mfma_scale_f32_16x16x128_f8f6f4 v[94:97], v[2:9], v[198:205], v[94:97], v219, v220 op_sel_hi:[0,0,0]
	v_mfma_scale_f32_16x16x128_f8f6f4 v[86:89], v[10:17], v[198:205], v[86:89], v219, v220 op_sel_hi:[0,0,0]
	s_setprio 0
	s_barrier
	s_add_i32 s18, 0, 0x1c000
	s_add_i32 s19, s41, s22
	v_add_u32_e32 v173, s18, v170
	v_lshl_add_u64 v[162:163], v[162:163], 0, s[46:47]
	s_mov_b32 m0, s19
	ds_read_b128 v[206:209], v173
	ds_read_b128 v[210:213], v173 offset:1024
	ds_read_b128 v[226:229], v173 offset:2048
	ds_read_b128 v[230:233], v173 offset:3072
	global_load_lds_dwordx4 v[162:163], off
	v_lshl_add_u64 v[162:163], v[164:165], 0, s[46:47]
	s_add_i32 m0, s19, 0x2000
	s_nop 0
	global_load_lds_dwordx4 v[162:163], off
	s_barrier
	s_waitcnt lgkmcnt(0)
	s_setprio 1
	s_waitcnt lgkmcnt(0)
	v_mfma_scale_f32_16x16x128_f8f6f4 v[138:141], v[206:213], v[174:181], v[138:141], v219, v220 op_sel_hi:[0,0,0]
	v_mfma_scale_f32_16x16x128_f8f6f4 v[130:133], v[226:233], v[174:181], v[130:133], v219, v220 op_sel_hi:[0,0,0]
	v_mfma_scale_f32_16x16x128_f8f6f4 v[122:125], v[206:213], v[182:189], v[122:125], v219, v220 op_sel_hi:[0,0,0]
	v_mfma_scale_f32_16x16x128_f8f6f4 v[114:117], v[226:233], v[182:189], v[114:117], v219, v220 op_sel_hi:[0,0,0]
	v_mfma_scale_f32_16x16x128_f8f6f4 v[106:109], v[206:213], v[190:197], v[106:109], v219, v220 op_sel_hi:[0,0,0]
	v_mfma_scale_f32_16x16x128_f8f6f4 v[98:101], v[226:233], v[190:197], v[98:101], v219, v220 op_sel_hi:[0,0,0]
	v_mfma_scale_f32_16x16x128_f8f6f4 v[90:93], v[206:213], v[198:205], v[90:93], v219, v220 op_sel_hi:[0,0,0]
	v_mfma_scale_f32_16x16x128_f8f6f4 v[82:85], v[226:233], v[198:205], v[82:85], v219, v220 op_sel_hi:[0,0,0]
	s_setprio 0
	s_mov_b32 m0, s28
	v_lshl_add_u64 v[162:163], v[166:167], 0, s[46:47]
	s_barrier
	ds_read_b128 v[174:177], v172 offset:49152
	ds_read_b128 v[178:181], v172 offset:50176
	ds_read_b128 v[182:185], v172 offset:51200
	ds_read_b128 v[186:189], v172 offset:52224
	ds_read_b128 v[190:193], v172 offset:53248
	ds_read_b128 v[194:197], v172 offset:54272
	ds_read_b128 v[198:201], v172 offset:55296
	ds_read_b128 v[202:205], v172 offset:56320
	global_load_lds_dwordx4 v[162:163], off
	v_lshl_add_u64 v[162:163], v[168:169], 0, s[46:47]
	s_mov_b32 m0, s29
	s_nop 0
	global_load_lds_dwordx4 v[162:163], off
	s_barrier
	s_waitcnt lgkmcnt(0)
	s_setprio 1
	s_waitcnt lgkmcnt(0)
	v_mfma_scale_f32_16x16x128_f8f6f4 v[78:81], v[2:9], v[174:181], v[78:81], v219, v220 op_sel_hi:[0,0,0]
	v_mfma_scale_f32_16x16x128_f8f6f4 v[70:73], v[10:17], v[174:181], v[70:73], v219, v220 op_sel_hi:[0,0,0]
	v_mfma_scale_f32_16x16x128_f8f6f4 v[62:65], v[2:9], v[182:189], v[62:65], v219, v220 op_sel_hi:[0,0,0]
	v_mfma_scale_f32_16x16x128_f8f6f4 v[54:57], v[10:17], v[182:189], v[54:57], v219, v220 op_sel_hi:[0,0,0]
	v_mfma_scale_f32_16x16x128_f8f6f4 v[46:49], v[2:9], v[190:197], v[46:49], v219, v220 op_sel_hi:[0,0,0]
	v_mfma_scale_f32_16x16x128_f8f6f4 v[38:41], v[10:17], v[190:197], v[38:41], v219, v220 op_sel_hi:[0,0,0]
	v_mfma_scale_f32_16x16x128_f8f6f4 v[30:33], v[2:9], v[198:205], v[30:33], v219, v220 op_sel_hi:[0,0,0]
	v_mfma_scale_f32_16x16x128_f8f6f4 v[22:25], v[10:17], v[198:205], v[22:25], v219, v220 op_sel_hi:[0,0,0]
	s_setprio 0
	s_barrier
	s_add_u32 s16, s16, 0x20080
	s_addc_u32 s17, s17, 0
	s_add_i32 s18, s18, s22
	s_mov_b32 m0, s18
	s_nop 0
	global_load_lds_dwordx4 v154, s[16:17]
	s_add_i32 m0, s18, 0x2000
	s_nop 0
	global_load_lds_dwordx4 v142, s[16:17]
	s_waitcnt vmcnt(6)
	s_barrier
	s_setprio 1
	v_mfma_scale_f32_16x16x128_f8f6f4 v[74:77], v[206:213], v[174:181], v[74:77], v219, v220 op_sel_hi:[0,0,0]
	v_mfma_scale_f32_16x16x128_f8f6f4 v[66:69], v[226:233], v[174:181], v[66:69], v219, v220 op_sel_hi:[0,0,0]
	v_mfma_scale_f32_16x16x128_f8f6f4 v[58:61], v[206:213], v[182:189], v[58:61], v219, v220 op_sel_hi:[0,0,0]
	v_mfma_scale_f32_16x16x128_f8f6f4 v[50:53], v[226:233], v[182:189], v[50:53], v219, v220 op_sel_hi:[0,0,0]
	v_mfma_scale_f32_16x16x128_f8f6f4 v[42:45], v[206:213], v[190:197], v[42:45], v219, v220 op_sel_hi:[0,0,0]
	v_mfma_scale_f32_16x16x128_f8f6f4 v[34:37], v[226:233], v[190:197], v[34:37], v219, v220 op_sel_hi:[0,0,0]
	v_mfma_scale_f32_16x16x128_f8f6f4 v[26:29], v[206:213], v[198:205], v[26:29], v219, v220 op_sel_hi:[0,0,0]
	v_mfma_scale_f32_16x16x128_f8f6f4 v[18:21], v[226:233], v[198:205], v[18:21], v219, v220 op_sel_hi:[0,0,0]
	s_setprio 0
	s_add_u32 s14, s14, 0x100
	s_addc_u32 s15, s15, 0
	s_add_u32 s38, s38, 0x100
	s_addc_u32 s39, s39, 0
	s_cmp_ge_i32 s40, s27
	s_mov_b32 s16, s40
	s_cbranch_scc0 .LBB0_1281
	s_barrier
	v_readlane_b32 s38, v255, 8
	s_mov_b32 s37, s59
	v_mov_b32_e32 v203, v214
	v_readlane_b32 s39, v255, 9
	s_branch .LBB0_1276

.LBB0_1345:
	s_ashr_i32 s5, s4, 31
	s_lshl_b64 s[10:11], s[4:5], 19
	v_readlane_b32 s12, v253, 46
	v_readlane_b32 s13, v253, 47
	s_add_u32 s10, s12, s10
	s_addc_u32 s11, s13, s11
	s_ashr_i32 s7, s6, 31
	s_lshl_b64 s[12:13], s[6:7], 19
	s_add_u32 s12, s20, s12
	s_addc_u32 s13, s21, s13
	s_andn2_b64 vcc, exec, s[0:1]
	s_cbranch_vccnz .Lzk_6
	s_and_b64 s[18:19], s[18:19], exec
	s_cselect_b32 s5, s11, s15
	s_cselect_b32 s7, s10, s14
	s_cselect_b32 s36, s13, s17
	s_cselect_b32 s37, s12, s16
	s_add_u32 s14, s14, 0x40080
	s_addc_u32 s15, s15, 0
	s_add_u32 s38, s16, 0x100
	v_mov_b32_e32 v18, 0
	v_mov_b32_e32 v218, 0xff800000
	v_mov_b32_e32 v214, 0xffffff80
	s_addc_u32 s39, s17, 0
	s_mov_b32 s16, 0
	v_mov_b32_e32 v19, v18
	v_mov_b32_e32 v20, v18
	v_mov_b32_e32 v21, v18
	v_mov_b32_e32 v22, v18
	v_mov_b32_e32 v23, v18
	v_mov_b32_e32 v24, v18
	v_mov_b32_e32 v25, v18
	v_mov_b32_e32 v34, v18
	v_mov_b32_e32 v35, v18
	v_mov_b32_e32 v36, v18
	v_mov_b32_e32 v37, v18
	v_mov_b32_e32 v38, v18
	v_mov_b32_e32 v39, v18
	v_mov_b32_e32 v40, v18
	v_mov_b32_e32 v41, v18
	v_mov_b32_e32 v50, v18
	v_mov_b32_e32 v51, v18
	v_mov_b32_e32 v52, v18
	v_mov_b32_e32 v53, v18
	v_mov_b32_e32 v54, v18
	v_mov_b32_e32 v55, v18
	v_mov_b32_e32 v56, v18
	v_mov_b32_e32 v57, v18
	v_mov_b32_e32 v66, v18
	v_mov_b32_e32 v67, v18
	v_mov_b32_e32 v68, v18
	v_mov_b32_e32 v69, v18
	v_mov_b32_e32 v70, v18
	v_mov_b32_e32 v71, v18
	v_mov_b32_e32 v72, v18
	v_mov_b32_e32 v73, v18
	v_mov_b32_e32 v26, v18
	v_mov_b32_e32 v27, v18
	v_mov_b32_e32 v28, v18
	v_mov_b32_e32 v29, v18
	v_mov_b32_e32 v30, v18
	v_mov_b32_e32 v31, v18
	v_mov_b32_e32 v32, v18
	v_mov_b32_e32 v33, v18
	v_mov_b32_e32 v42, v18
	v_mov_b32_e32 v43, v18
	v_mov_b32_e32 v44, v18
	v_mov_b32_e32 v45, v18
	v_mov_b32_e32 v46, v18
	v_mov_b32_e32 v47, v18
	v_mov_b32_e32 v48, v18
	v_mov_b32_e32 v49, v18
	v_mov_b32_e32 v58, v18
	v_mov_b32_e32 v59, v18
	v_mov_b32_e32 v60, v18
	v_mov_b32_e32 v61, v18
	v_mov_b32_e32 v62, v18
	v_mov_b32_e32 v63, v18
	v_mov_b32_e32 v64, v18
	v_mov_b32_e32 v65, v18
	v_mov_b32_e32 v74, v18
	v_mov_b32_e32 v75, v18
	v_mov_b32_e32 v76, v18
	v_mov_b32_e32 v77, v18
	v_mov_b32_e32 v78, v18
	v_mov_b32_e32 v79, v18
	v_mov_b32_e32 v80, v18
	v_mov_b32_e32 v81, v18
	v_mov_b32_e32 v82, v18
	v_mov_b32_e32 v83, v18
	v_mov_b32_e32 v84, v18
	v_mov_b32_e32 v85, v18
	v_mov_b32_e32 v86, v18
	v_mov_b32_e32 v87, v18
	v_mov_b32_e32 v88, v18
	v_mov_b32_e32 v89, v18
	v_mov_b32_e32 v98, v18
	v_mov_b32_e32 v99, v18
	v_mov_b32_e32 v100, v18
	v_mov_b32_e32 v101, v18
	v_mov_b32_e32 v102, v18
	v_mov_b32_e32 v103, v18
	v_mov_b32_e32 v104, v18
	v_mov_b32_e32 v105, v18
	v_mov_b32_e32 v114, v18
	v_mov_b32_e32 v115, v18
	v_mov_b32_e32 v116, v18
	v_mov_b32_e32 v117, v18
	v_mov_b32_e32 v118, v18
	v_mov_b32_e32 v119, v18
	v_mov_b32_e32 v120, v18
	v_mov_b32_e32 v121, v18
	v_mov_b32_e32 v130, v18
	v_mov_b32_e32 v131, v18
	v_mov_b32_e32 v132, v18
	v_mov_b32_e32 v133, v18
	v_mov_b32_e32 v134, v18
	v_mov_b32_e32 v135, v18
	v_mov_b32_e32 v136, v18
	v_mov_b32_e32 v137, v18
	v_mov_b32_e32 v90, v18
	v_mov_b32_e32 v91, v18
	v_mov_b32_e32 v92, v18
	v_mov_b32_e32 v93, v18
	v_mov_b32_e32 v94, v18
	v_mov_b32_e32 v95, v18
	v_mov_b32_e32 v96, v18
	v_mov_b32_e32 v97, v18
	v_mov_b32_e32 v106, v18
	v_mov_b32_e32 v107, v18
	v_mov_b32_e32 v108, v18
	v_mov_b32_e32 v109, v18
	v_mov_b32_e32 v110, v18
	v_mov_b32_e32 v111, v18
	v_mov_b32_e32 v112, v18
	v_mov_b32_e32 v113, v18
	v_mov_b32_e32 v122, v18
	v_mov_b32_e32 v123, v18
	v_mov_b32_e32 v124, v18
	v_mov_b32_e32 v125, v18
	v_mov_b32_e32 v126, v18
	v_mov_b32_e32 v127, v18
	v_mov_b32_e32 v128, v18
	v_mov_b32_e32 v129, v18
	v_mov_b32_e32 v148, v18
	v_mov_b32_e32 v149, v18
	v_mov_b32_e32 v150, v18
	v_mov_b32_e32 v151, v18
	v_mov_b32_e32 v138, v18
	v_mov_b32_e32 v139, v18
	v_mov_b32_e32 v140, v18
	v_mov_b32_e32 v141, v18
	s_mov_b64 s[46:47], 0x80
	s_branch .Lrot_5

.Lrot_5:
	s_add_i32 s40, s16, 2
	s_add_u32 s17, s14, 0xfffc0080
	s_addc_u32 s18, s15, -1
	s_add_i32 s41, 0, 0x10000
	v_add_u32_e32 v14, s41, v170
	ds_read_b128 v[2:5], v14
	ds_read_b128 v[6:9], v14 offset:1024
	ds_read_b128 v[10:13], v14 offset:2048
	ds_read_b128 v[14:17], v14 offset:3072
	s_cmp_eq_u32 s30, s16
	s_cselect_b32 s16, s37, s38
	s_cselect_b32 s19, s5, s18
	s_cselect_b32 s18, s7, s17
	s_cselect_b32 s17, s36, s39
	s_add_i32 m0, s23, 0xc000
	ds_read_b128 v[174:177], v172
	ds_read_b128 v[178:181], v172 offset:1024
	ds_read_b128 v[182:185], v172 offset:2048
	ds_read_b128 v[186:189], v172 offset:3072
	ds_read_b128 v[190:193], v172 offset:4096
	ds_read_b128 v[194:197], v172 offset:5120
	ds_read_b128 v[198:201], v172 offset:6144
	ds_read_b128 v[202:205], v172 offset:7168
	global_load_lds_dwordx4 v158, s[14:15]
	s_add_i32 m0, s23, 0xe000
	s_nop 0
	global_load_lds_dwordx4 v160, s[14:15]
	s_waitcnt lgkmcnt(8)
	s_barrier
	s_waitcnt lgkmcnt(0)
	s_setprio 1
	s_waitcnt lgkmcnt(0)
	v_mfma_scale_f32_16x16x128_f8f6f4 v[138:141], v[2:9], v[174:181], v[138:141], v219, v221 op_sel_hi:[0,0,0]
	v_mfma_scale_f32_16x16x128_f8f6f4 v[148:151], v[10:17], v[174:181], v[148:151], v219, v221 op_sel_hi:[0,0,0]
	v_mfma_scale_f32_16x16x128_f8f6f4 v[126:129], v[2:9], v[182:189], v[126:129], v219, v221 op_sel_hi:[0,0,0]
	v_mfma_scale_f32_16x16x128_f8f6f4 v[122:125], v[10:17], v[182:189], v[122:125], v219, v221 op_sel_hi:[0,0,0]
	v_mfma_scale_f32_16x16x128_f8f6f4 v[110:113], v[2:9], v[190:197], v[110:113], v219, v221 op_sel_hi:[0,0,0]
	v_mfma_scale_f32_16x16x128_f8f6f4 v[106:109], v[10:17], v[190:197], v[106:109], v219, v221 op_sel_hi:[0,0,0]
	v_mfma_scale_f32_16x16x128_f8f6f4 v[94:97], v[2:9], v[198:205], v[94:97], v219, v221 op_sel_hi:[0,0,0]
	v_mfma_scale_f32_16x16x128_f8f6f4 v[90:93], v[10:17], v[198:205], v[90:93], v219, v221 op_sel_hi:[0,0,0]
	s_setprio 0
	s_barrier
	s_add_i32 s44, 0, 0x14000
	v_add_u32_e32 v162, s44, v170
	s_add_i32 s41, s41, s22
	ds_read_b128 v[206:209], v162
	ds_read_b128 v[210:213], v162 offset:1024
	ds_read_b128 v[226:229], v162 offset:2048
	ds_read_b128 v[230:233], v162 offset:3072
	v_lshl_add_u64 v[162:163], s[16:17], 0, v[154:155]
	s_mov_b32 m0, s41
	v_lshl_add_u64 v[164:165], s[16:17], 0, v[142:143]
	global_load_lds_dwordx4 v[162:163], off
	s_add_i32 m0, s41, 0x2000
	s_nop 0
	global_load_lds_dwordx4 v[164:165], off
	s_barrier
	s_waitcnt lgkmcnt(0)
	s_setprio 1
	s_waitcnt lgkmcnt(0)
	v_mfma_scale_f32_16x16x128_f8f6f4 v[134:137], v[206:213], v[174:181], v[134:137], v219, v221 op_sel_hi:[0,0,0]
	v_mfma_scale_f32_16x16x128_f8f6f4 v[130:133], v[226:233], v[174:181], v[130:133], v219, v221 op_sel_hi:[0,0,0]
	v_mfma_scale_f32_16x16x128_f8f6f4 v[118:121], v[206:213], v[182:189], v[118:121], v219, v221 op_sel_hi:[0,0,0]
	v_mfma_scale_f32_16x16x128_f8f6f4 v[114:117], v[226:233], v[182:189], v[114:117], v219, v221 op_sel_hi:[0,0,0]
	v_mfma_scale_f32_16x16x128_f8f6f4 v[102:105], v[206:213], v[190:197], v[102:105], v219, v221 op_sel_hi:[0,0,0]
	v_mfma_scale_f32_16x16x128_f8f6f4 v[98:101], v[226:233], v[190:197], v[98:101], v219, v221 op_sel_hi:[0,0,0]
	v_mfma_scale_f32_16x16x128_f8f6f4 v[86:89], v[206:213], v[198:205], v[86:89], v219, v221 op_sel_hi:[0,0,0]
	v_mfma_scale_f32_16x16x128_f8f6f4 v[82:85], v[226:233], v[198:205], v[82:85], v219, v221 op_sel_hi:[0,0,0]
	s_setprio 0
	s_mov_b32 m0, s23
	v_lshl_add_u64 v[166:167], s[18:19], 0, v[156:157]
	s_barrier
	ds_read_b128 v[174:177], v172 offset:16384
	ds_read_b128 v[178:181], v172 offset:17408
	ds_read_b128 v[182:185], v172 offset:18432
	ds_read_b128 v[186:189], v172 offset:19456
	ds_read_b128 v[190:193], v172 offset:20480
	ds_read_b128 v[194:197], v172 offset:21504
	ds_read_b128 v[198:201], v172 offset:22528
	ds_read_b128 v[202:205], v172 offset:23552
	global_load_lds_dwordx4 v[166:167], off
	v_lshl_add_u64 v[168:169], s[18:19], 0, v[152:153]
	s_mov_b32 m0, s24
	s_nop 0
	global_load_lds_dwordx4 v[168:169], off
	s_barrier
	s_waitcnt lgkmcnt(0)
	s_setprio 1
	s_waitcnt lgkmcnt(0)
	v_mfma_scale_f32_16x16x128_f8f6f4 v[78:81], v[2:9], v[174:181], v[78:81], v219, v221 op_sel_hi:[0,0,0]
	v_mfma_scale_f32_16x16x128_f8f6f4 v[74:77], v[10:17], v[174:181], v[74:77], v219, v221 op_sel_hi:[0,0,0]
	v_mfma_scale_f32_16x16x128_f8f6f4 v[62:65], v[2:9], v[182:189], v[62:65], v219, v221 op_sel_hi:[0,0,0]
	v_mfma_scale_f32_16x16x128_f8f6f4 v[58:61], v[10:17], v[182:189], v[58:61], v219, v221 op_sel_hi:[0,0,0]
	v_mfma_scale_f32_16x16x128_f8f6f4 v[46:49], v[2:9], v[190:197], v[46:49], v219, v221 op_sel_hi:[0,0,0]
	v_mfma_scale_f32_16x16x128_f8f6f4 v[42:45], v[10:17], v[190:197], v[42:45], v219, v221 op_sel_hi:[0,0,0]
	v_mfma_scale_f32_16x16x128_f8f6f4 v[30:33], v[2:9], v[198:205], v[30:33], v219, v221 op_sel_hi:[0,0,0]
	v_mfma_scale_f32_16x16x128_f8f6f4 v[26:29], v[10:17], v[198:205], v[26:29], v219, v221 op_sel_hi:[0,0,0]
	s_setprio 0
	s_barrier
	s_add_u32 s42, s16, 0x40000
	s_addc_u32 s43, s17, 0
	s_add_i32 s41, s44, s22
	s_mov_b32 m0, s41
	s_nop 0
	global_load_lds_dwordx4 v154, s[42:43]
	s_add_i32 m0, s41, 0x2000
	s_nop 0
	global_load_lds_dwordx4 v142, s[42:43]
	s_waitcnt vmcnt(6)
	s_barrier
	s_setprio 1
	v_mfma_scale_f32_16x16x128_f8f6f4 v[70:73], v[206:213], v[174:181], v[70:73], v219, v221 op_sel_hi:[0,0,0]
	v_mfma_scale_f32_16x16x128_f8f6f4 v[66:69], v[226:233], v[174:181], v[66:69], v219, v221 op_sel_hi:[0,0,0]
	v_mfma_scale_f32_16x16x128_f8f6f4 v[54:57], v[206:213], v[182:189], v[54:57], v219, v221 op_sel_hi:[0,0,0]
	v_mfma_scale_f32_16x16x128_f8f6f4 v[50:53], v[226:233], v[182:189], v[50:53], v219, v221 op_sel_hi:[0,0,0]
	v_mfma_scale_f32_16x16x128_f8f6f4 v[38:41], v[206:213], v[190:197], v[38:41], v219, v221 op_sel_hi:[0,0,0]
	v_mfma_scale_f32_16x16x128_f8f6f4 v[34:37], v[226:233], v[190:197], v[34:37], v219, v221 op_sel_hi:[0,0,0]
	v_mfma_scale_f32_16x16x128_f8f6f4 v[22:25], v[206:213], v[198:205], v[22:25], v219, v221 op_sel_hi:[0,0,0]
	v_mfma_scale_f32_16x16x128_f8f6f4 v[18:21], v[226:233], v[198:205], v[18:21], v219, v221 op_sel_hi:[0,0,0]
	s_setprio 0
	s_add_i32 s41, 0, 0x18000
	v_add_u32_e32 v14, s41, v170
	s_barrier
	ds_read_b128 v[2:5], v14
	ds_read_b128 v[6:9], v14 offset:1024
	ds_read_b128 v[10:13], v14 offset:2048
	ds_read_b128 v[14:17], v14 offset:3072
	s_add_u32 s18, s18, 0x40000
	s_addc_u32 s19, s19, 0
	s_mov_b32 m0, s25
	ds_read_b128 v[174:177], v172 offset:32768
	ds_read_b128 v[178:181], v172 offset:33792
	ds_read_b128 v[182:185], v172 offset:34816
	ds_read_b128 v[186:189], v172 offset:35840
	ds_read_b128 v[190:193], v172 offset:36864
	ds_read_b128 v[194:197], v172 offset:37888
	ds_read_b128 v[198:201], v172 offset:38912
	ds_read_b128 v[202:205], v172 offset:39936
	global_load_lds_dwordx4 v156, s[18:19]
	s_mov_b32 m0, s26
	s_nop 0
	global_load_lds_dwordx4 v152, s[18:19]
	s_waitcnt lgkmcnt(8)
	s_barrier
	s_waitcnt lgkmcnt(0)
	s_setprio 1
	s_waitcnt lgkmcnt(0)
	v_mfma_scale_f32_16x16x128_f8f6f4 v[138:141], v[2:9], v[174:181], v[138:141], v219, v221 op_sel_hi:[0,0,0]
	v_mfma_scale_f32_16x16x128_f8f6f4 v[148:151], v[10:17], v[174:181], v[148:151], v219, v221 op_sel_hi:[0,0,0]
	v_mfma_scale_f32_16x16x128_f8f6f4 v[126:129], v[2:9], v[182:189], v[126:129], v219, v221 op_sel_hi:[0,0,0]
	v_mfma_scale_f32_16x16x128_f8f6f4 v[122:125], v[10:17], v[182:189], v[122:125], v219, v221 op_sel_hi:[0,0,0]
	v_mfma_scale_f32_16x16x128_f8f6f4 v[110:113], v[2:9], v[190:197], v[110:113], v219, v221 op_sel_hi:[0,0,0]
	v_mfma_scale_f32_16x16x128_f8f6f4 v[106:109], v[10:17], v[190:197], v[106:109], v219, v221 op_sel_hi:[0,0,0]
	v_mfma_scale_f32_16x16x128_f8f6f4 v[94:97], v[2:9], v[198:205], v[94:97], v219, v221 op_sel_hi:[0,0,0]
	v_mfma_scale_f32_16x16x128_f8f6f4 v[90:93], v[10:17], v[198:205], v[90:93], v219, v221 op_sel_hi:[0,0,0]
	s_setprio 0
	s_barrier
	s_add_i32 s18, 0, 0x1c000
	s_add_i32 s19, s41, s22
	v_add_u32_e32 v173, s18, v170
	v_lshl_add_u64 v[162:163], v[162:163], 0, s[46:47]
	s_mov_b32 m0, s19
	ds_read_b128 v[206:209], v173
	ds_read_b128 v[210:213], v173 offset:1024
	ds_read_b128 v[226:229], v173 offset:2048
	ds_read_b128 v[230:233], v173 offset:3072
	global_load_lds_dwordx4 v[162:163], off
	v_lshl_add_u64 v[162:163], v[164:165], 0, s[46:47]
	s_add_i32 m0, s19, 0x2000
	s_nop 0
	global_load_lds_dwordx4 v[162:163], off
	s_barrier
	s_waitcnt lgkmcnt(0)
	s_setprio 1
	s_waitcnt lgkmcnt(0)
	v_mfma_scale_f32_16x16x128_f8f6f4 v[134:137], v[206:213], v[174:181], v[134:137], v219, v221 op_sel_hi:[0,0,0]
	v_mfma_scale_f32_16x16x128_f8f6f4 v[130:133], v[226:233], v[174:181], v[130:133], v219, v221 op_sel_hi:[0,0,0]
	v_mfma_scale_f32_16x16x128_f8f6f4 v[118:121], v[206:213], v[182:189], v[118:121], v219, v221 op_sel_hi:[0,0,0]
	v_mfma_scale_f32_16x16x128_f8f6f4 v[114:117], v[226:233], v[182:189], v[114:117], v219, v221 op_sel_hi:[0,0,0]
	v_mfma_scale_f32_16x16x128_f8f6f4 v[102:105], v[206:213], v[190:197], v[102:105], v219, v221 op_sel_hi:[0,0,0]
	v_mfma_scale_f32_16x16x128_f8f6f4 v[98:101], v[226:233], v[190:197], v[98:101], v219, v221 op_sel_hi:[0,0,0]
	v_mfma_scale_f32_16x16x128_f8f6f4 v[86:89], v[206:213], v[198:205], v[86:89], v219, v221 op_sel_hi:[0,0,0]
	v_mfma_scale_f32_16x16x128_f8f6f4 v[82:85], v[226:233], v[198:205], v[82:85], v219, v221 op_sel_hi:[0,0,0]
	s_setprio 0
	s_mov_b32 m0, s28
	v_lshl_add_u64 v[162:163], v[166:167], 0, s[46:47]
	s_barrier
	ds_read_b128 v[174:177], v172 offset:49152
	ds_read_b128 v[178:181], v172 offset:50176
	ds_read_b128 v[182:185], v172 offset:51200
	ds_read_b128 v[186:189], v172 offset:52224
	ds_read_b128 v[190:193], v172 offset:53248
	ds_read_b128 v[194:197], v172 offset:54272
	ds_read_b128 v[198:201], v172 offset:55296
	ds_read_b128 v[202:205], v172 offset:56320
	global_load_lds_dwordx4 v[162:163], off
	v_lshl_add_u64 v[162:163], v[168:169], 0, s[46:47]
	s_mov_b32 m0, s29
	s_nop 0
	global_load_lds_dwordx4 v[162:163], off
	s_barrier
	s_waitcnt lgkmcnt(0)
	s_setprio 1
	s_waitcnt lgkmcnt(0)
	v_mfma_scale_f32_16x16x128_f8f6f4 v[78:81], v[2:9], v[174:181], v[78:81], v219, v221 op_sel_hi:[0,0,0]
	v_mfma_scale_f32_16x16x128_f8f6f4 v[74:77], v[10:17], v[174:181], v[74:77], v219, v221 op_sel_hi:[0,0,0]
	v_mfma_scale_f32_16x16x128_f8f6f4 v[62:65], v[2:9], v[182:189], v[62:65], v219, v221 op_sel_hi:[0,0,0]
	v_mfma_scale_f32_16x16x128_f8f6f4 v[58:61], v[10:17], v[182:189], v[58:61], v219, v221 op_sel_hi:[0,0,0]
	v_mfma_scale_f32_16x16x128_f8f6f4 v[46:49], v[2:9], v[190:197], v[46:49], v219, v221 op_sel_hi:[0,0,0]
	v_mfma_scale_f32_16x16x128_f8f6f4 v[42:45], v[10:17], v[190:197], v[42:45], v219, v221 op_sel_hi:[0,0,0]
	v_mfma_scale_f32_16x16x128_f8f6f4 v[30:33], v[2:9], v[198:205], v[30:33], v219, v221 op_sel_hi:[0,0,0]
	v_mfma_scale_f32_16x16x128_f8f6f4 v[26:29], v[10:17], v[198:205], v[26:29], v219, v221 op_sel_hi:[0,0,0]
	s_setprio 0
	s_barrier
	s_add_u32 s16, s16, 0x40080
	s_addc_u32 s17, s17, 0
	s_add_i32 s18, s18, s22
	s_mov_b32 m0, s18
	s_nop 0
	global_load_lds_dwordx4 v154, s[16:17]
	s_add_i32 m0, s18, 0x2000
	s_nop 0
	global_load_lds_dwordx4 v142, s[16:17]
	s_waitcnt vmcnt(6)
	s_barrier
	s_setprio 1
	v_mfma_scale_f32_16x16x128_f8f6f4 v[70:73], v[206:213], v[174:181], v[70:73], v219, v221 op_sel_hi:[0,0,0]
	v_mfma_scale_f32_16x16x128_f8f6f4 v[66:69], v[226:233], v[174:181], v[66:69], v219, v221 op_sel_hi:[0,0,0]
	v_mfma_scale_f32_16x16x128_f8f6f4 v[54:57], v[206:213], v[182:189], v[54:57], v219, v221 op_sel_hi:[0,0,0]
	v_mfma_scale_f32_16x16x128_f8f6f4 v[50:53], v[226:233], v[182:189], v[50:53], v219, v221 op_sel_hi:[0,0,0]
	v_mfma_scale_f32_16x16x128_f8f6f4 v[38:41], v[206:213], v[190:197], v[38:41], v219, v221 op_sel_hi:[0,0,0]
	v_mfma_scale_f32_16x16x128_f8f6f4 v[34:37], v[226:233], v[190:197], v[34:37], v219, v221 op_sel_hi:[0,0,0]
	v_mfma_scale_f32_16x16x128_f8f6f4 v[22:25], v[206:213], v[198:205], v[22:25], v219, v221 op_sel_hi:[0,0,0]
	v_mfma_scale_f32_16x16x128_f8f6f4 v[18:21], v[226:233], v[198:205], v[18:21], v219, v221 op_sel_hi:[0,0,0]
	s_setprio 0
	s_add_u32 s14, s14, 0x100
	s_addc_u32 s15, s15, 0
	s_add_u32 s38, s38, 0x100
	s_addc_u32 s39, s39, 0
	s_cmp_ge_i32 s40, s27
	s_mov_b32 s16, s40
	s_cbranch_scc0 .LBB0_1347
	s_barrier
	v_readlane_b32 s38, v255, 8
	s_mov_b32 s37, s59
	v_mov_b32_e32 v203, v214
	v_readlane_b32 s39, v255, 9
	s_branch .LBB0_1342
